# sc1 write-through on swiglu and residual X epilogue stores
# speedup vs baseline: 1.0046x; 1.0046x over previous
; __device__ __forceinline__ unsigned cvt_pk_bf16(float lo, float hi) { unsigned r; asm volatile("v_cvt_pk_bf16_f32 %0, %1, %2" : "=v"(r) : "v"(lo), "v"(hi)); return r; }
;     __device__ __forceinline__ void operator()(const f32x4 (&acc)[2][2][4][2], const Unit& u, int wr, int wc, int fr, int fq) const {
;     ...
;         const int row0 = u.pm * BM + wr * 64 + fr, col0 = u.pn * HALF + wc * 32 + 8 * fq;
; #pragma unroll
;         for (int ai = 0; ai < 2; ++ai)
; #pragma unroll
;             for (int m = 0; m < 4; ++m) { bf16_t* rowp = O + (size_t)(row0 + ai * HALF + m * 16) * ldc + col0;
;                 float v[8];
; #pragma unroll
;                 for (int n = 0; n < 2; ++n)
; #pragma unroll
;                     for (int j = 0; j < 4; ++j) { const float g = acc[ai][0][m][n][j], up = acc[ai][1][m][n][j];
;                         v[n * 4 + j] = g * __builtin_amdgcn_rcpf(1.0f + __expf(-g)) * up; }
;                 u32x4 w; w.x = cvt_pk_bf16(v[0], v[1]); w.y = cvt_pk_bf16(v[2], v[3]); w.z = cvt_pk_bf16(v[4], v[5]); w.w = cvt_pk_bf16(v[6], v[7]);
;                 if (NT_ACT) __builtin_nontemporal_store(w, (u32x4*)rowp); else *(u32x4*)rowp = w; }
.LBB0_586:
	v_mul_f32_e32 v150, 0xbfb8aa3b, v126
	v_exp_f32_e32 v150, v150
	v_lshl_or_b32 v146, s51, 7, v143
	v_lshl_add_u32 v145, s52, 8, v141
	v_ashrrev_i32_e32 v147, 31, v146
	v_add_f32_e32 v150, 1.0, v150
	v_rcp_f32_e32 v150, v150
	v_mov_b64_e32 v[138:139], s[74:75]
	s_movk_i32 s11, 0x2c00
	v_mad_i64_i32 v[148:149], s[20:21], v145, s11, v[138:139]
	v_mul_f32_e32 v126, v126, v150
	v_mul_f32_e32 v122, v126, v122
	v_mul_f32_e32 v126, 0xbfb8aa3b, v127
	v_exp_f32_e32 v126, v126
	s_andn2_b64 vcc, exec, s[14:15]
	s_movk_i32 s25, 0x1600
	s_movk_i32 s24, 0x410
	v_add_f32_e32 v126, 1.0, v126
	v_rcp_f32_e32 v126, v126
	s_nop 0
	v_mul_f32_e32 v126, v127, v126
	v_mul_f32_e32 v123, v126, v123
	v_mul_f32_e32 v126, 0xbfb8aa3b, v128
	v_exp_f32_e32 v126, v126
	s_nop 0
	v_add_f32_e32 v126, 1.0, v126
	v_rcp_f32_e32 v126, v126
	s_nop 0
	v_mul_f32_e32 v126, v128, v126
	v_mul_f32_e32 v124, v126, v124
	v_mul_f32_e32 v126, 0xbfb8aa3b, v129
	v_exp_f32_e32 v126, v126
	s_nop 0
	v_add_f32_e32 v126, 1.0, v126
	v_rcp_f32_e32 v126, v126
	s_nop 0
	v_mul_f32_e32 v126, v129, v126
	v_mul_f32_e32 v125, v126, v125
	v_mul_f32_e32 v126, 0xbfb8aa3b, v118
	v_exp_f32_e32 v126, v126
	s_nop 0
	v_add_f32_e32 v126, 1.0, v126
	v_rcp_f32_e32 v126, v126
	s_nop 0
	v_mul_f32_e32 v118, v118, v126
	v_mul_f32_e32 v118, v118, v114
	v_mul_f32_e32 v114, 0xbfb8aa3b, v119
	v_exp_f32_e32 v114, v114
	s_nop 0
	v_add_f32_e32 v114, 1.0, v114
	v_rcp_f32_e32 v114, v114
	s_nop 0
	v_mul_f32_e32 v114, v119, v114
	v_mul_f32_e32 v119, v114, v115
	v_mul_f32_e32 v114, 0xbfb8aa3b, v120
	v_exp_f32_e32 v114, v114
	s_nop 0
	v_add_f32_e32 v114, 1.0, v114
	v_rcp_f32_e32 v114, v114
	s_nop 0
	v_mul_f32_e32 v114, v120, v114
	v_mul_f32_e32 v126, v114, v116
	v_mul_f32_e32 v114, 0xbfb8aa3b, v121
	v_exp_f32_e32 v114, v114
	v_cvt_pk_bf16_f32 v116, v122, v123
	s_nop 0
	v_add_f32_e32 v114, 1.0, v114
	v_rcp_f32_e32 v114, v114
	s_nop 0
	v_mul_f32_e32 v114, v121, v114
	v_mul_f32_e32 v127, v114, v117
	v_lshlrev_b64 v[114:115], 1, v[146:147]
	v_lshl_add_u64 v[120:121], v[148:149], 0, v[114:115]
	v_cvt_pk_bf16_f32 v117, v124, v125
	v_cvt_pk_bf16_f32 v118, v118, v119
	v_cvt_pk_bf16_f32 v119, v126, v127
	global_store_dwordx4 v[120:121], v[116:119], off sc1
	s_nop 1
	v_mul_f32_e32 v118, 0xbfb8aa3b, v110
	v_exp_f32_e32 v118, v118
	v_or_b32_e32 v116, 16, v145
	v_mad_i64_i32 v[116:117], s[20:21], v116, s11, v[138:139]
	v_add_f32_e32 v118, 1.0, v118
	v_rcp_f32_e32 v118, v118
	s_nop 0
	v_mul_f32_e32 v110, v110, v118
	v_mul_f32_e32 v106, v110, v106
	v_mul_f32_e32 v110, 0xbfb8aa3b, v111
	v_exp_f32_e32 v110, v110
	s_nop 0
	v_add_f32_e32 v110, 1.0, v110
	v_rcp_f32_e32 v110, v110
	s_nop 0
	v_mul_f32_e32 v110, v111, v110
	v_mul_f32_e32 v107, v110, v107
	v_mul_f32_e32 v110, 0xbfb8aa3b, v112
	v_exp_f32_e32 v110, v110
	s_nop 0
	v_add_f32_e32 v110, 1.0, v110
	v_rcp_f32_e32 v110, v110
	s_nop 0
	v_mul_f32_e32 v110, v112, v110
	v_mul_f32_e32 v108, v110, v108
	v_mul_f32_e32 v110, 0xbfb8aa3b, v113
	v_exp_f32_e32 v110, v110
	s_nop 0
	v_add_f32_e32 v110, 1.0, v110
	v_rcp_f32_e32 v110, v110
	s_nop 0
	v_mul_f32_e32 v110, v113, v110
	v_mul_f32_e32 v109, v110, v109
	v_mul_f32_e32 v110, 0xbfb8aa3b, v102
	v_exp_f32_e32 v110, v110
	s_nop 0
	v_add_f32_e32 v110, 1.0, v110
	v_rcp_f32_e32 v110, v110
	s_nop 0
	v_mul_f32_e32 v102, v102, v110
	v_mul_f32_e32 v110, v102, v98
	v_mul_f32_e32 v98, 0xbfb8aa3b, v103
	v_exp_f32_e32 v98, v98
	s_nop 0
	v_add_f32_e32 v98, 1.0, v98
	v_rcp_f32_e32 v98, v98
	s_nop 0
	v_mul_f32_e32 v98, v103, v98
	v_mul_f32_e32 v111, v98, v99
	v_mul_f32_e32 v98, 0xbfb8aa3b, v104
	v_exp_f32_e32 v98, v98
	v_lshl_add_u64 v[102:103], v[116:117], 0, v[114:115]
	v_add_f32_e32 v98, 1.0, v98
	v_rcp_f32_e32 v98, v98
	s_nop 0
	v_mul_f32_e32 v98, v104, v98
	v_mul_f32_e32 v104, v98, v100
	v_mul_f32_e32 v98, 0xbfb8aa3b, v105
	v_exp_f32_e32 v98, v98
	s_nop 0
	v_add_f32_e32 v98, 1.0, v98
	v_rcp_f32_e32 v98, v98
	s_nop 0
	v_mul_f32_e32 v98, v105, v98
	v_mul_f32_e32 v101, v98, v101
	v_cvt_pk_bf16_f32 v98, v106, v107
	v_cvt_pk_bf16_f32 v99, v108, v109
	v_cvt_pk_bf16_f32 v100, v110, v111
	v_cvt_pk_bf16_f32 v101, v104, v101
	global_store_dwordx4 v[102:103], v[98:101], off sc1
	s_nop 1
	v_mul_f32_e32 v100, 0xbfb8aa3b, v94
	v_exp_f32_e32 v100, v100
	v_or_b32_e32 v98, 32, v145
	v_mad_i64_i32 v[98:99], s[20:21], v98, s11, v[138:139]
	v_add_f32_e32 v100, 1.0, v100
	v_rcp_f32_e32 v100, v100
	s_nop 0
	v_mul_f32_e32 v94, v94, v100
	v_mul_f32_e32 v90, v94, v90
	v_mul_f32_e32 v94, 0xbfb8aa3b, v95
	v_exp_f32_e32 v94, v94
	s_nop 0
	v_add_f32_e32 v94, 1.0, v94
	v_rcp_f32_e32 v94, v94
	s_nop 0
	v_mul_f32_e32 v94, v95, v94
	v_mul_f32_e32 v91, v94, v91
	v_mul_f32_e32 v94, 0xbfb8aa3b, v96
	v_exp_f32_e32 v94, v94
	s_nop 0
	v_add_f32_e32 v94, 1.0, v94
	v_rcp_f32_e32 v94, v94
	s_nop 0
	v_mul_f32_e32 v94, v96, v94
	v_mul_f32_e32 v92, v94, v92
	v_mul_f32_e32 v94, 0xbfb8aa3b, v97
	v_exp_f32_e32 v94, v94
	s_nop 0
	v_add_f32_e32 v94, 1.0, v94
	v_rcp_f32_e32 v94, v94
	s_nop 0
	v_mul_f32_e32 v94, v97, v94
	v_mul_f32_e32 v93, v94, v93
	v_mul_f32_e32 v94, 0xbfb8aa3b, v86
	v_exp_f32_e32 v94, v94
	s_nop 0
	v_add_f32_e32 v94, 1.0, v94
	v_rcp_f32_e32 v94, v94
	s_nop 0
	v_mul_f32_e32 v86, v86, v94
	v_mul_f32_e32 v94, v86, v82
	v_mul_f32_e32 v82, 0xbfb8aa3b, v87
	v_exp_f32_e32 v82, v82
	s_nop 0
	v_add_f32_e32 v82, 1.0, v82
	v_rcp_f32_e32 v82, v82
	s_nop 0
	v_mul_f32_e32 v82, v87, v82
	v_mul_f32_e32 v95, v82, v83
	v_mul_f32_e32 v82, 0xbfb8aa3b, v88
	v_exp_f32_e32 v82, v82
	v_lshl_add_u64 v[86:87], v[98:99], 0, v[114:115]
	v_add_f32_e32 v82, 1.0, v82
	v_rcp_f32_e32 v82, v82
	s_nop 0
	v_mul_f32_e32 v82, v88, v82
	v_mul_f32_e32 v88, v82, v84
	v_mul_f32_e32 v82, 0xbfb8aa3b, v89
	v_exp_f32_e32 v82, v82
; __device__ __forceinline__ unsigned cvt_pk_bf16(float lo, float hi) { unsigned r; asm volatile("v_cvt_pk_bf16_f32 %0, %1, %2" : "=v"(r) : "v"(lo), "v"(hi)); return r; }
;     __device__ __forceinline__ void operator()(const f32x4 (&acc)[2][2][4][2], const Unit& u, int wr, int wc, int fr, int fq) const {
;     ...
;             for (int m = 0; m < 4; ++m) { bf16_t* rowp = O + (size_t)(row0 + ai * HALF + m * 16) * ldc + col0;
;                 float v[8];
; #pragma unroll
;                 for (int n = 0; n < 2; ++n)
; #pragma unroll
;                     for (int j = 0; j < 4; ++j) { const float g = acc[ai][0][m][n][j], up = acc[ai][1][m][n][j];
;                         v[n * 4 + j] = g * __builtin_amdgcn_rcpf(1.0f + __expf(-g)) * up; }
;                 u32x4 w; w.x = cvt_pk_bf16(v[0], v[1]); w.y = cvt_pk_bf16(v[2], v[3]); w.z = cvt_pk_bf16(v[4], v[5]); w.w = cvt_pk_bf16(v[6], v[7]);
;                 if (NT_ACT) __builtin_nontemporal_store(w, (u32x4*)rowp); else *(u32x4*)rowp = w; }
	s_nop 0
	v_add_f32_e32 v82, 1.0, v82
	v_rcp_f32_e32 v82, v82
	s_nop 0
	v_mul_f32_e32 v82, v89, v82
	v_mul_f32_e32 v85, v82, v85
	v_cvt_pk_bf16_f32 v82, v90, v91
	v_cvt_pk_bf16_f32 v83, v92, v93
	v_cvt_pk_bf16_f32 v84, v94, v95
	v_cvt_pk_bf16_f32 v85, v88, v85
	global_store_dwordx4 v[86:87], v[82:85], off sc1
	s_nop 1
	v_mul_f32_e32 v84, 0xbfb8aa3b, v78
	v_exp_f32_e32 v84, v84
	v_or_b32_e32 v82, 48, v145
	v_mad_i64_i32 v[82:83], s[20:21], v82, s11, v[138:139]
	v_add_f32_e32 v84, 1.0, v84
	v_rcp_f32_e32 v84, v84
	s_nop 0
	v_mul_f32_e32 v78, v78, v84
	v_mul_f32_e32 v74, v78, v74
	v_mul_f32_e32 v78, 0xbfb8aa3b, v79
	v_exp_f32_e32 v78, v78
	s_nop 0
	v_add_f32_e32 v78, 1.0, v78
	v_rcp_f32_e32 v78, v78
	s_nop 0
	v_mul_f32_e32 v78, v79, v78
	v_mul_f32_e32 v75, v78, v75
	v_mul_f32_e32 v78, 0xbfb8aa3b, v80
	v_exp_f32_e32 v78, v78
	s_nop 0
	v_add_f32_e32 v78, 1.0, v78
	v_rcp_f32_e32 v78, v78
	s_nop 0
	v_mul_f32_e32 v78, v80, v78
	v_mul_f32_e32 v76, v78, v76
	v_mul_f32_e32 v78, 0xbfb8aa3b, v81
	v_exp_f32_e32 v78, v78
	s_nop 0
	v_add_f32_e32 v78, 1.0, v78
	v_rcp_f32_e32 v78, v78
	s_nop 0
	v_mul_f32_e32 v78, v81, v78
	v_mul_f32_e32 v77, v78, v77
	v_mul_f32_e32 v78, 0xbfb8aa3b, v70
	v_exp_f32_e32 v78, v78
	s_nop 0
	v_add_f32_e32 v78, 1.0, v78
	v_rcp_f32_e32 v78, v78
	s_nop 0
	v_mul_f32_e32 v70, v70, v78
	v_mul_f32_e32 v78, v70, v66
	v_mul_f32_e32 v66, 0xbfb8aa3b, v71
	v_exp_f32_e32 v66, v66
	s_nop 0
	v_add_f32_e32 v66, 1.0, v66
	v_rcp_f32_e32 v66, v66
	s_nop 0
	v_mul_f32_e32 v66, v71, v66
	v_mul_f32_e32 v79, v66, v67
	v_mul_f32_e32 v66, 0xbfb8aa3b, v72
	v_exp_f32_e32 v66, v66
	v_lshl_add_u64 v[70:71], v[82:83], 0, v[114:115]
	v_add_f32_e32 v66, 1.0, v66
	v_rcp_f32_e32 v66, v66
	s_nop 0
	v_mul_f32_e32 v66, v72, v66
	v_mul_f32_e32 v72, v66, v68
	v_mul_f32_e32 v66, 0xbfb8aa3b, v73
	v_exp_f32_e32 v66, v66
	s_nop 0
	v_add_f32_e32 v66, 1.0, v66
	v_rcp_f32_e32 v66, v66
	s_nop 0
	v_mul_f32_e32 v66, v73, v66
	v_mul_f32_e32 v69, v66, v69
	v_cvt_pk_bf16_f32 v66, v74, v75
	v_cvt_pk_bf16_f32 v67, v76, v77
	v_cvt_pk_bf16_f32 v68, v78, v79
	v_cvt_pk_bf16_f32 v69, v72, v69
	global_store_dwordx4 v[70:71], v[66:69], off sc1
	s_nop 1
	v_mul_f32_e32 v68, 0xbfb8aa3b, v62
	v_exp_f32_e32 v68, v68
	v_add_u32_e32 v66, 0x80, v145
	v_mad_i64_i32 v[66:67], s[20:21], v66, s11, v[138:139]
	v_add_f32_e32 v68, 1.0, v68
	v_rcp_f32_e32 v68, v68
	s_nop 0
	v_mul_f32_e32 v62, v62, v68
	v_mul_f32_e32 v58, v62, v58
	v_mul_f32_e32 v62, 0xbfb8aa3b, v63
	v_exp_f32_e32 v62, v62
	s_nop 0
	v_add_f32_e32 v62, 1.0, v62
	v_rcp_f32_e32 v62, v62
	s_nop 0
	v_mul_f32_e32 v62, v63, v62
	v_mul_f32_e32 v59, v62, v59
	v_mul_f32_e32 v62, 0xbfb8aa3b, v64
	v_exp_f32_e32 v62, v62
	s_nop 0
	v_add_f32_e32 v62, 1.0, v62
	v_rcp_f32_e32 v62, v62
	s_nop 0
	v_mul_f32_e32 v62, v64, v62
	v_mul_f32_e32 v60, v62, v60
	v_mul_f32_e32 v62, 0xbfb8aa3b, v65
	v_exp_f32_e32 v62, v62
	s_nop 0
	v_add_f32_e32 v62, 1.0, v62
	v_rcp_f32_e32 v62, v62
	s_nop 0
	v_mul_f32_e32 v62, v65, v62
	v_mul_f32_e32 v61, v62, v61
	v_mul_f32_e32 v62, 0xbfb8aa3b, v54
	v_exp_f32_e32 v62, v62
	s_nop 0
	v_add_f32_e32 v62, 1.0, v62
	v_rcp_f32_e32 v62, v62
	s_nop 0
	v_mul_f32_e32 v54, v54, v62
	v_mul_f32_e32 v62, v54, v50
	v_mul_f32_e32 v50, 0xbfb8aa3b, v55
	v_exp_f32_e32 v50, v50
	s_nop 0
	v_add_f32_e32 v50, 1.0, v50
	v_rcp_f32_e32 v50, v50
	s_nop 0
	v_mul_f32_e32 v50, v55, v50
	v_mul_f32_e32 v63, v50, v51
	v_mul_f32_e32 v50, 0xbfb8aa3b, v56
	v_exp_f32_e32 v50, v50
	v_lshl_add_u64 v[54:55], v[66:67], 0, v[114:115]
	v_add_f32_e32 v50, 1.0, v50
	v_rcp_f32_e32 v50, v50
	s_nop 0
	v_mul_f32_e32 v50, v56, v50
	v_mul_f32_e32 v56, v50, v52
	v_mul_f32_e32 v50, 0xbfb8aa3b, v57
	v_exp_f32_e32 v50, v50
	s_nop 0
	v_add_f32_e32 v50, 1.0, v50
	v_rcp_f32_e32 v50, v50
	s_nop 0
	v_mul_f32_e32 v50, v57, v50
	v_mul_f32_e32 v53, v50, v53
	v_cvt_pk_bf16_f32 v50, v58, v59
	v_cvt_pk_bf16_f32 v51, v60, v61
	v_cvt_pk_bf16_f32 v52, v62, v63
	v_cvt_pk_bf16_f32 v53, v56, v53
	global_store_dwordx4 v[54:55], v[50:53], off sc1
	s_nop 1
	v_mul_f32_e32 v52, 0xbfb8aa3b, v46
	v_exp_f32_e32 v52, v52
	v_add_u32_e32 v50, 0x90, v145
	v_mad_i64_i32 v[50:51], s[20:21], v50, s11, v[138:139]
	v_add_f32_e32 v52, 1.0, v52
	v_rcp_f32_e32 v52, v52
	s_nop 0
	v_mul_f32_e32 v46, v46, v52
	v_mul_f32_e32 v42, v46, v42
	v_mul_f32_e32 v46, 0xbfb8aa3b, v47
	v_exp_f32_e32 v46, v46
	s_nop 0
	v_add_f32_e32 v46, 1.0, v46
	v_rcp_f32_e32 v46, v46
	s_nop 0
	v_mul_f32_e32 v46, v47, v46
	v_mul_f32_e32 v43, v46, v43
	v_mul_f32_e32 v46, 0xbfb8aa3b, v48
	v_exp_f32_e32 v46, v46
	s_nop 0
	v_add_f32_e32 v46, 1.0, v46
	v_rcp_f32_e32 v46, v46
	s_nop 0
	v_mul_f32_e32 v46, v48, v46
	v_mul_f32_e32 v44, v46, v44
	v_mul_f32_e32 v46, 0xbfb8aa3b, v49
	v_exp_f32_e32 v46, v46
	s_nop 0
	v_add_f32_e32 v46, 1.0, v46
	v_rcp_f32_e32 v46, v46
	s_nop 0
; __device__ __forceinline__ unsigned cvt_pk_bf16(float lo, float hi) { unsigned r; asm volatile("v_cvt_pk_bf16_f32 %0, %1, %2" : "=v"(r) : "v"(lo), "v"(hi)); return r; }
; #define PG8_BAR __builtin_amdgcn_s_barrier()
;     __device__ __forceinline__ void operator()(const f32x4 (&acc)[2][2][4][2], const Unit& u, int wr, int wc, int fr, int fq) const {
;     ...
;             for (int m = 0; m < 4; ++m) { bf16_t* rowp = O + (size_t)(row0 + ai * HALF + m * 16) * ldc + col0;
;                 float v[8];
; #pragma unroll
;                 for (int n = 0; n < 2; ++n)
; #pragma unroll
;                     for (int j = 0; j < 4; ++j) { const float g = acc[ai][0][m][n][j], up = acc[ai][1][m][n][j];
;                         v[n * 4 + j] = g * __builtin_amdgcn_rcpf(1.0f + __expf(-g)) * up; }
;                 u32x4 w; w.x = cvt_pk_bf16(v[0], v[1]); w.y = cvt_pk_bf16(v[2], v[3]); w.z = cvt_pk_bf16(v[4], v[5]); w.w = cvt_pk_bf16(v[6], v[7]);
;                 if (NT_ACT) __builtin_nontemporal_store(w, (u32x4*)rowp); else *(u32x4*)rowp = w; }
;     ...
;         if constexpr (ALIGN_EPI) { if (wr == 0) PG8_BAR; }
;         if constexpr (!Epi::AFTER_DRAIN) { E(acc, cur, wr, wc, fr, fq); S.done(cur); }
;         else { if (has_next) { E(acc, cur, wr, wc, fr, fq); S.done(cur); } }
;         if (!has_next) break;
; #pragma unroll
;         for (int a = 0; a < 2; ++a)
; #pragma unroll
;             for (int b = 0; b < 2; ++b)
; #pragma unroll
;                 for (int m = 0; m < 4; ++m)
; #pragma unroll
;                     for (int n = 0; n < 2; ++n) acc[a][b][m][n] = (f32x4){0.f, 0.f, 0.f, 0.f};
;         cur = nxt; cA = nA; cB = nB; ++ui;
;         if constexpr (ALIGN_EPI) { if (wr == 1) PG8_BAR; }
	v_mul_f32_e32 v46, v49, v46
	v_mul_f32_e32 v45, v46, v45
	v_mul_f32_e32 v46, 0xbfb8aa3b, v38
	v_exp_f32_e32 v46, v46
	s_nop 0
	v_add_f32_e32 v46, 1.0, v46
	v_rcp_f32_e32 v46, v46
	s_nop 0
	v_mul_f32_e32 v38, v38, v46
	v_mul_f32_e32 v46, v38, v34
	v_mul_f32_e32 v34, 0xbfb8aa3b, v39
	v_exp_f32_e32 v34, v34
	s_nop 0
	v_add_f32_e32 v34, 1.0, v34
	v_rcp_f32_e32 v34, v34
	s_nop 0
	v_mul_f32_e32 v34, v39, v34
	v_mul_f32_e32 v47, v34, v35
	v_mul_f32_e32 v34, 0xbfb8aa3b, v40
	v_exp_f32_e32 v34, v34
	v_lshl_add_u64 v[38:39], v[50:51], 0, v[114:115]
	v_add_f32_e32 v34, 1.0, v34
	v_rcp_f32_e32 v34, v34
	s_nop 0
	v_mul_f32_e32 v34, v40, v34
	v_mul_f32_e32 v40, v34, v36
	v_mul_f32_e32 v34, 0xbfb8aa3b, v41
	v_exp_f32_e32 v34, v34
	s_nop 0
	v_add_f32_e32 v34, 1.0, v34
	v_rcp_f32_e32 v34, v34
	s_nop 0
	v_mul_f32_e32 v34, v41, v34
	v_mul_f32_e32 v37, v34, v37
	v_cvt_pk_bf16_f32 v34, v42, v43
	v_cvt_pk_bf16_f32 v35, v44, v45
	v_cvt_pk_bf16_f32 v36, v46, v47
	v_cvt_pk_bf16_f32 v37, v40, v37
	global_store_dwordx4 v[38:39], v[34:37], off sc1
	s_nop 1
	v_mul_f32_e32 v36, 0xbfb8aa3b, v30
	v_exp_f32_e32 v36, v36
	v_add_u32_e32 v34, 0xa0, v145
	v_mad_i64_i32 v[34:35], s[20:21], v34, s11, v[138:139]
	v_add_f32_e32 v36, 1.0, v36
	v_rcp_f32_e32 v36, v36
	s_nop 0
	v_mul_f32_e32 v30, v30, v36
	v_mul_f32_e32 v26, v30, v26
	v_mul_f32_e32 v30, 0xbfb8aa3b, v31
	v_exp_f32_e32 v30, v30
	s_nop 0
	v_add_f32_e32 v30, 1.0, v30
	v_rcp_f32_e32 v30, v30
	s_nop 0
	v_mul_f32_e32 v30, v31, v30
	v_mul_f32_e32 v27, v30, v27
	v_mul_f32_e32 v30, 0xbfb8aa3b, v32
	v_exp_f32_e32 v30, v30
	s_nop 0
	v_add_f32_e32 v30, 1.0, v30
	v_rcp_f32_e32 v30, v30
	s_nop 0
	v_mul_f32_e32 v30, v32, v30
	v_mul_f32_e32 v28, v30, v28
	v_mul_f32_e32 v30, 0xbfb8aa3b, v33
	v_exp_f32_e32 v30, v30
	s_nop 0
	v_add_f32_e32 v30, 1.0, v30
	v_rcp_f32_e32 v30, v30
	s_nop 0
	v_mul_f32_e32 v30, v33, v30
	v_mul_f32_e32 v29, v30, v29
	v_mul_f32_e32 v30, 0xbfb8aa3b, v22
	v_exp_f32_e32 v30, v30
	s_nop 0
	v_add_f32_e32 v30, 1.0, v30
	v_rcp_f32_e32 v30, v30
	s_nop 0
	v_mul_f32_e32 v22, v22, v30
	v_mul_f32_e32 v30, v22, v18
	v_mul_f32_e32 v18, 0xbfb8aa3b, v23
	v_exp_f32_e32 v18, v18
	s_nop 0
	v_add_f32_e32 v18, 1.0, v18
	v_rcp_f32_e32 v18, v18
	s_nop 0
	v_mul_f32_e32 v18, v23, v18
	v_mul_f32_e32 v31, v18, v19
	v_mul_f32_e32 v18, 0xbfb8aa3b, v24
	v_exp_f32_e32 v18, v18
	v_lshl_add_u64 v[22:23], v[34:35], 0, v[114:115]
	v_add_f32_e32 v18, 1.0, v18
	v_rcp_f32_e32 v18, v18
	s_nop 0
	v_mul_f32_e32 v18, v24, v18
	v_mul_f32_e32 v24, v18, v20
	v_mul_f32_e32 v18, 0xbfb8aa3b, v25
	v_exp_f32_e32 v18, v18
	s_nop 0
	v_add_f32_e32 v18, 1.0, v18
	v_rcp_f32_e32 v18, v18
	s_nop 0
	v_mul_f32_e32 v18, v25, v18
	v_mul_f32_e32 v21, v18, v21
	v_cvt_pk_bf16_f32 v18, v26, v27
	v_cvt_pk_bf16_f32 v19, v28, v29
	v_cvt_pk_bf16_f32 v20, v30, v31
	v_cvt_pk_bf16_f32 v21, v24, v21
	global_store_dwordx4 v[22:23], v[18:21], off sc1
	s_nop 1
	v_mul_f32_e32 v20, 0xbfb8aa3b, v14
	v_exp_f32_e32 v20, v20
	v_add_u32_e32 v18, 0xb0, v145
	v_mad_i64_i32 v[18:19], s[20:21], v18, s11, v[138:139]
	v_add_f32_e32 v20, 1.0, v20
	v_rcp_f32_e32 v20, v20
	s_mov_b64 s[20:21], -1
	v_mul_f32_e32 v14, v14, v20
	v_mul_f32_e32 v10, v14, v10
	v_mul_f32_e32 v14, 0xbfb8aa3b, v15
	v_exp_f32_e32 v14, v14
	s_nop 0
	v_add_f32_e32 v14, 1.0, v14
	v_rcp_f32_e32 v14, v14
	s_nop 0
	v_mul_f32_e32 v14, v15, v14
	v_mul_f32_e32 v11, v14, v11
	v_mul_f32_e32 v14, 0xbfb8aa3b, v16
	v_exp_f32_e32 v14, v14
	s_nop 0
	v_add_f32_e32 v14, 1.0, v14
	v_rcp_f32_e32 v14, v14
	s_nop 0
	v_mul_f32_e32 v14, v16, v14
	v_mul_f32_e32 v12, v14, v12
	v_mul_f32_e32 v14, 0xbfb8aa3b, v17
	v_exp_f32_e32 v14, v14
	s_nop 0
	v_add_f32_e32 v14, 1.0, v14
	v_rcp_f32_e32 v14, v14
	s_nop 0
	v_mul_f32_e32 v14, v17, v14
	v_mul_f32_e32 v13, v14, v13
	v_mul_f32_e32 v14, 0xbfb8aa3b, v6
	v_exp_f32_e32 v14, v14
	s_nop 0
	v_add_f32_e32 v14, 1.0, v14
	v_rcp_f32_e32 v14, v14
	s_nop 0
	v_mul_f32_e32 v6, v6, v14
	v_mul_f32_e32 v14, v6, v2
	v_mul_f32_e32 v2, 0xbfb8aa3b, v7
	v_exp_f32_e32 v2, v2
	s_nop 0
	v_add_f32_e32 v2, 1.0, v2
	v_rcp_f32_e32 v2, v2
	s_nop 0
	v_mul_f32_e32 v2, v7, v2
	v_mul_f32_e32 v15, v2, v3
	v_mul_f32_e32 v2, 0xbfb8aa3b, v8
	v_exp_f32_e32 v2, v2
	v_lshl_add_u64 v[6:7], v[18:19], 0, v[114:115]
	v_add_f32_e32 v2, 1.0, v2
	v_rcp_f32_e32 v2, v2
	s_nop 0
	v_mul_f32_e32 v2, v8, v2
	v_mul_f32_e32 v8, v2, v4
	v_mul_f32_e32 v2, 0xbfb8aa3b, v9
	v_exp_f32_e32 v2, v2
	s_nop 0
	v_add_f32_e32 v2, 1.0, v2
	v_rcp_f32_e32 v2, v2
	s_nop 0
	v_mul_f32_e32 v2, v9, v2
	v_mul_f32_e32 v5, v2, v5
	v_cvt_pk_bf16_f32 v2, v10, v11
	v_cvt_pk_bf16_f32 v3, v12, v13
	v_cvt_pk_bf16_f32 v4, v14, v15
	v_cvt_pk_bf16_f32 v5, v8, v5
	global_store_dwordx4 v[6:7], v[2:5], off sc1
	s_cbranch_vccnz .LBB0_557
	s_andn2_b64 vcc, exec, s[6:7]
	s_cbranch_vccnz .LBB0_556
	s_barrier
	s_branch .LBB0_556

; __device__ __forceinline__ unsigned cvt_pk_bf16(float lo, float hi) { unsigned r; asm volatile("v_cvt_pk_bf16_f32 %0, %1, %2" : "=v"(r) : "v"(lo), "v"(hi)); return r; }
;     __device__ __forceinline__ void fused(f32x4 (&acc)[2][2][4][2], const Unit& u, int wr, int wc, int fr, int fq, PG8_LAS unsigned char* lds, int wid, int lane) const {
;     ...
;         const float poison = bad ? __builtin_nanf("") : 0.0f;
;         f32x4 vs[2][2], vh[2][2];
; #pragma unroll
;         for (int bj = 0; bj < 2; ++bj)
; #pragma unroll
;             for (int n = 0; n < 2; ++n) { vs[bj][n] = write_h ? *(const f32x4*)(cb + 2048 + bj * HALF + 4 * n) : (f32x4){0.f, 0.f, 0.f, 0.f}; vh[bj][n] = write_h ? *(const f32x4*)(cb + 4096 + bj * HALF + 4 * n) : (f32x4){0.f, 0.f, 0.f, 0.f}; }
; #pragma unroll
;         for (int ai = 0; ai < 2; ++ai)
; #pragma unroll
;             for (int m = 0; m < 4; ++m) { const int r = ai * HALF + wr * 64 + m * 16 + fr; const float rs = write_h ? S[r] : 0.0f; const size_t off = (size_t)(u.pm * BM + r) * 2048 + col0;
; #pragma unroll
;                 for (int bj = 0; bj < 2; ++bj) { const f32x4 x0 = acc[ai][bj][m][0] + poison, x1 = acc[ai][bj][m][1] + poison;
;                     if (out) { if (wofs == 0) { *(f32x4*)(out + off + bj * HALF) = x0; *(f32x4*)(out + off + bj * HALF + 4) = x1; } }
;                     else { u32x4 w; w.x = cvt_pk_bf16(x0[0], x0[1]); w.y = cvt_pk_bf16(x0[2], x0[3]); w.z = cvt_pk_bf16(x1[0], x1[1]); w.w = cvt_pk_bf16(x1[2], x1[3]); if (NT_FX) __builtin_nontemporal_store(w, (u32x4*)(X + wofs + off + bj * HALF)); else *(u32x4*)(X + wofs + off + bj * HALF) = w; }
;                     if (write_h) { const f32x4 h0 = x0 * rs * vs[bj][0] + vh[bj][0], h1 = x1 * rs * vs[bj][1] + vh[bj][1];
;                         u32x4 w; w.x = cvt_pk_bf16(h0[0], h0[1]); w.y = cvt_pk_bf16(h0[2], h0[3]); w.z = cvt_pk_bf16(h1[0], h1[1]); w.w = cvt_pk_bf16(h1[2], h1[3]); if (NT_FH) __builtin_nontemporal_store(w, (u32x4*)(H + wofs + off + bj * HALF)); else *(u32x4*)(H + wofs + off + bj * HALF) = w; } }
;                 asm volatile("" ::: "memory"); }
.LBB0_973:
	s_or_b64 exec, exec, s[0:1]
	s_mov_b64 s[0:1], 0x4000
	s_waitcnt lgkmcnt(1)
	v_lshl_add_u64 v[130:131], v[204:205], 0, s[0:1]
	s_mov_b64 s[0:1], 0x2000
	v_add_co_u32_e32 v138, vcc, 0x2000, v204
	v_lshl_add_u64 v[132:133], v[204:205], 0, s[0:1]
	s_nop 0
	v_addc_co_u32_e32 v139, vcc, 0, v205, vcc
	s_mov_b64 s[0:1], 0x4200
	s_waitcnt lgkmcnt(0)
	s_barrier
	v_add_co_u32_e32 v142, vcc, 0x4000, v204
	v_lshl_add_u64 v[134:135], v[204:205], 0, s[0:1]
	s_mov_b64 s[0:1], 0x2200
	v_addc_co_u32_e32 v143, vcc, 0, v205, vcc
	global_load_dwordx4 v[146:149], v[132:133], off offset:16
	global_load_dwordx4 v[150:153], v[130:131], off offset:16
	v_lshl_add_u64 v[130:131], v[204:205], 0, s[0:1]
	global_load_dwordx4 v[130:133], v[130:131], off offset:16
	s_nop 0
	global_load_dwordx4 v[134:137], v[134:135], off offset:16
	s_nop 0
	global_load_dwordx4 v[154:157], v[142:143], off
	global_load_dwordx4 v[158:161], v[138:139], off
	s_nop 0
	global_load_dwordx4 v[138:141], v[138:139], off offset:512
	s_nop 0
	global_load_dwordx4 v[142:145], v[142:143], off offset:512
	ds_read_b32 v170, v231 offset:4096
	s_waitcnt lgkmcnt(1)
	v_or_b32_e32 v162, v162, v235
	v_lshlrev_b64 v[164:165], 11, v[202:203]
	v_cmp_eq_u32_e32 vcc, 0, v162
	v_mov_b32_e32 v162, 0x7fc00000
	v_lshl_add_u64 v[164:165], v[164:165], 0, v[200:201]
	v_readlane_b32 s0, v251, 0
	v_cndmask_b32_e64 v162, v162, 0, vcc
	v_lshlrev_b64 v[164:165], 1, v[164:165]
	v_readlane_b32 s1, v251, 1
	v_pk_add_f32 v[172:173], v[100:101], v[162:163] op_sel_hi:[1,0]
	v_pk_add_f32 v[176:177], v[98:99], v[162:163] op_sel_hi:[1,0]
	v_pk_add_f32 v[104:105], v[104:105], v[162:163] op_sel_hi:[1,0]
	v_pk_add_f32 v[102:103], v[102:103], v[162:163] op_sel_hi:[1,0]
	v_cvt_pk_bf16_f32 v98, v176, v177
	v_cvt_pk_bf16_f32 v99, v172, v173
	v_lshl_add_u64 v[178:179], s[0:1], 0, v[164:165]
	v_cvt_pk_bf16_f32 v100, v102, v103
	v_cvt_pk_bf16_f32 v101, v104, v105
	global_store_dwordx4 v[178:179], v[98:101], off sc1
	s_waitcnt lgkmcnt(0)
	v_pk_mul_f32 v[102:103], v[102:103], v[170:171] op_sel_hi:[1,0]
	v_pk_mul_f32 v[104:105], v[104:105], v[170:171] op_sel_hi:[1,0]
	v_pk_mul_f32 v[98:99], v[176:177], v[170:171] op_sel_hi:[1,0]
	v_pk_mul_f32 v[100:101], v[172:173], v[170:171] op_sel_hi:[1,0]
	v_pk_add_f32 v[108:109], v[108:109], v[162:163] op_sel_hi:[1,0]
	v_pk_add_f32 v[106:107], v[106:107], v[162:163] op_sel_hi:[1,0]
	v_pk_add_f32 v[112:113], v[112:113], v[162:163] op_sel_hi:[1,0]
	v_pk_add_f32 v[110:111], v[110:111], v[162:163] op_sel_hi:[1,0]
	v_lshl_add_u64 v[164:165], s[94:95], 0, v[164:165]
	v_pk_mul_f32 v[172:173], v[106:107], v[170:171] op_sel_hi:[1,0]
	v_pk_mul_f32 v[176:177], v[108:109], v[170:171] op_sel_hi:[1,0]
	v_pk_mul_f32 v[184:185], v[110:111], v[170:171] op_sel_hi:[1,0]
	v_pk_mul_f32 v[170:171], v[112:113], v[170:171] op_sel_hi:[1,0]
	v_lshlrev_b64 v[168:169], 11, v[208:209]
	v_lshl_add_u64 v[168:169], v[168:169], 0, v[200:201]
	v_lshlrev_b64 v[168:169], 1, v[168:169]
	v_pk_add_f32 v[128:129], v[128:129], v[162:163] op_sel_hi:[1,0]
	v_pk_add_f32 v[126:127], v[126:127], v[162:163] op_sel_hi:[1,0]
	v_pk_add_f32 v[124:125], v[124:125], v[162:163] op_sel_hi:[1,0]
	v_pk_add_f32 v[122:123], v[122:123], v[162:163] op_sel_hi:[1,0]
	v_lshl_add_u64 v[180:181], s[0:1], 0, v[168:169]
	v_pk_add_f32 v[96:97], v[96:97], v[162:163] op_sel_hi:[1,0]
	v_pk_add_f32 v[94:95], v[94:95], v[162:163] op_sel_hi:[1,0]
	v_pk_add_f32 v[88:89], v[88:89], v[162:163] op_sel_hi:[1,0]
	v_pk_add_f32 v[86:87], v[86:87], v[162:163] op_sel_hi:[1,0]
	v_pk_add_f32 v[80:81], v[80:81], v[162:163] op_sel_hi:[1,0]
	v_pk_add_f32 v[78:79], v[78:79], v[162:163] op_sel_hi:[1,0]
	v_pk_add_f32 v[72:73], v[72:73], v[162:163] op_sel_hi:[1,0]
	v_pk_add_f32 v[70:71], v[70:71], v[162:163] op_sel_hi:[1,0]
	v_pk_add_f32 v[64:65], v[64:65], v[162:163] op_sel_hi:[1,0]
	v_pk_add_f32 v[62:63], v[62:63], v[162:163] op_sel_hi:[1,0]
	v_pk_add_f32 v[56:57], v[56:57], v[162:163] op_sel_hi:[1,0]
	v_pk_add_f32 v[54:55], v[54:55], v[162:163] op_sel_hi:[1,0]
	v_pk_add_f32 v[48:49], v[48:49], v[162:163] op_sel_hi:[1,0]
	v_pk_add_f32 v[46:47], v[46:47], v[162:163] op_sel_hi:[1,0]
	v_pk_add_f32 v[40:41], v[40:41], v[162:163] op_sel_hi:[1,0]
	v_pk_add_f32 v[38:39], v[38:39], v[162:163] op_sel_hi:[1,0]
	v_pk_add_f32 v[32:33], v[32:33], v[162:163] op_sel_hi:[1,0]
	v_pk_add_f32 v[30:31], v[30:31], v[162:163] op_sel_hi:[1,0]
	v_pk_add_f32 v[24:25], v[24:25], v[162:163] op_sel_hi:[1,0]
	v_pk_add_f32 v[22:23], v[22:23], v[162:163] op_sel_hi:[1,0]
	v_pk_add_f32 v[16:17], v[16:17], v[162:163] op_sel_hi:[1,0]
	v_pk_add_f32 v[14:15], v[14:15], v[162:163] op_sel_hi:[1,0]
	v_pk_add_f32 v[8:9], v[8:9], v[162:163] op_sel_hi:[1,0]
	v_pk_add_f32 v[6:7], v[6:7], v[162:163] op_sel_hi:[1,0]
	s_add_i32 s18, s81, 2
	s_cmp_ge_i32 s18, s83
	s_waitcnt vmcnt(5)
	v_pk_fma_f32 v[170:171], v[132:133], v[170:171], v[136:137]
	v_pk_fma_f32 v[184:185], v[130:131], v[184:185], v[134:135]
	s_waitcnt vmcnt(3)
	v_pk_fma_f32 v[100:101], v[160:161], v[100:101], v[156:157]
	v_pk_fma_f32 v[98:99], v[158:159], v[98:99], v[154:155]
	v_pk_fma_f32 v[104:105], v[148:149], v[104:105], v[152:153]
	v_pk_fma_f32 v[102:103], v[146:147], v[102:103], v[150:151]
	v_cvt_pk_bf16_f32 v98, v98, v99
	v_cvt_pk_bf16_f32 v99, v100, v101
	s_waitcnt vmcnt(1)
; __device__ __forceinline__ unsigned cvt_pk_bf16(float lo, float hi) { unsigned r; asm volatile("v_cvt_pk_bf16_f32 %0, %1, %2" : "=v"(r) : "v"(lo), "v"(hi)); return r; }
;     __device__ __forceinline__ void fused(f32x4 (&acc)[2][2][4][2], const Unit& u, int wr, int wc, int fr, int fq, PG8_LAS unsigned char* lds, int wid, int lane) const {
;     ...
; #pragma unroll
;         for (int ai = 0; ai < 2; ++ai)
; #pragma unroll
;             for (int m = 0; m < 4; ++m) { const int r = ai * HALF + wr * 64 + m * 16 + fr; const float rs = write_h ? S[r] : 0.0f; const size_t off = (size_t)(u.pm * BM + r) * 2048 + col0;
; #pragma unroll
;                 for (int bj = 0; bj < 2; ++bj) { const f32x4 x0 = acc[ai][bj][m][0] + poison, x1 = acc[ai][bj][m][1] + poison;
;                     if (out) { if (wofs == 0) { *(f32x4*)(out + off + bj * HALF) = x0; *(f32x4*)(out + off + bj * HALF + 4) = x1; } }
;                     else { u32x4 w; w.x = cvt_pk_bf16(x0[0], x0[1]); w.y = cvt_pk_bf16(x0[2], x0[3]); w.z = cvt_pk_bf16(x1[0], x1[1]); w.w = cvt_pk_bf16(x1[2], x1[3]); if (NT_FX) __builtin_nontemporal_store(w, (u32x4*)(X + wofs + off + bj * HALF)); else *(u32x4*)(X + wofs + off + bj * HALF) = w; }
;                     if (write_h) { const f32x4 h0 = x0 * rs * vs[bj][0] + vh[bj][0], h1 = x1 * rs * vs[bj][1] + vh[bj][1];
;                         u32x4 w; w.x = cvt_pk_bf16(h0[0], h0[1]); w.y = cvt_pk_bf16(h0[2], h0[3]); w.z = cvt_pk_bf16(h1[0], h1[1]); w.w = cvt_pk_bf16(h1[2], h1[3]); if (NT_FH) __builtin_nontemporal_store(w, (u32x4*)(H + wofs + off + bj * HALF)); else *(u32x4*)(H + wofs + off + bj * HALF) = w; } }
;                 asm volatile("" ::: "memory"); }
	v_pk_fma_f32 v[176:177], v[140:141], v[176:177], v[144:145]
	v_cvt_pk_bf16_f32 v100, v102, v103
	v_cvt_pk_bf16_f32 v101, v104, v105
	global_store_dwordx4 v[164:165], v[98:101], off
	v_pk_fma_f32 v[172:173], v[138:139], v[172:173], v[142:143]
	s_nop 0
	v_cvt_pk_bf16_f32 v98, v106, v107
	v_cvt_pk_bf16_f32 v99, v108, v109
	v_cvt_pk_bf16_f32 v100, v110, v111
	v_cvt_pk_bf16_f32 v101, v112, v113
	global_store_dwordx4 v[178:179], v[98:101], off offset:256 sc1
	v_pk_add_f32 v[108:109], v[114:115], v[162:163] op_sel_hi:[1,0]
	v_pk_add_f32 v[110:111], v[120:121], v[162:163] op_sel_hi:[1,0]
	v_cvt_pk_bf16_f32 v98, v172, v173
	v_cvt_pk_bf16_f32 v99, v176, v177
	v_cvt_pk_bf16_f32 v100, v184, v185
	v_cvt_pk_bf16_f32 v101, v170, v171
	global_store_dwordx4 v[164:165], v[98:101], off offset:256
	ds_read_b32 v102, v231 offset:4160
	v_pk_add_f32 v[112:113], v[118:119], v[162:163] op_sel_hi:[1,0]
	v_cvt_pk_bf16_f32 v98, v126, v127
	v_cvt_pk_bf16_f32 v99, v128, v129
	v_cvt_pk_bf16_f32 v100, v122, v123
	v_cvt_pk_bf16_f32 v101, v124, v125
	global_store_dwordx4 v[180:181], v[98:101], off sc1
	s_waitcnt lgkmcnt(0)
	v_pk_mul_f32 v[104:105], v[122:123], v[102:103] op_sel_hi:[1,0]
	v_pk_mul_f32 v[106:107], v[124:125], v[102:103] op_sel_hi:[1,0]
	v_pk_mul_f32 v[98:99], v[126:127], v[102:103] op_sel_hi:[1,0]
	v_pk_mul_f32 v[100:101], v[128:129], v[102:103] op_sel_hi:[1,0]
	v_pk_fma_f32 v[98:99], v[158:159], v[98:99], v[154:155]
	v_pk_fma_f32 v[100:101], v[160:161], v[100:101], v[156:157]
	v_pk_fma_f32 v[104:105], v[146:147], v[104:105], v[150:151]
	v_pk_fma_f32 v[106:107], v[148:149], v[106:107], v[152:153]
	v_cvt_pk_bf16_f32 v98, v98, v99
	v_cvt_pk_bf16_f32 v99, v100, v101
	v_cvt_pk_bf16_f32 v100, v104, v105
	v_lshl_add_u64 v[104:105], s[94:95], 0, v[168:169]
	v_cvt_pk_bf16_f32 v101, v106, v107
	global_store_dwordx4 v[104:105], v[98:101], off
	v_pk_add_f32 v[106:107], v[116:117], v[162:163] op_sel_hi:[1,0]
	s_nop 0
	v_cvt_pk_bf16_f32 v98, v108, v109
	v_cvt_pk_bf16_f32 v99, v106, v107
	v_cvt_pk_bf16_f32 v100, v112, v113
	v_cvt_pk_bf16_f32 v101, v110, v111
	global_store_dwordx4 v[180:181], v[98:101], off offset:256 sc1
	s_nop 1
	v_pk_mul_f32 v[98:99], v[108:109], v[102:103] op_sel_hi:[1,0]
	v_pk_mul_f32 v[100:101], v[106:107], v[102:103] op_sel_hi:[1,0]
	v_pk_fma_f32 v[98:99], v[138:139], v[98:99], v[142:143]
	v_pk_fma_f32 v[100:101], v[140:141], v[100:101], v[144:145]
	v_pk_mul_f32 v[106:107], v[112:113], v[102:103] op_sel_hi:[1,0]
	v_pk_mul_f32 v[102:103], v[110:111], v[102:103] op_sel_hi:[1,0]
	v_pk_fma_f32 v[106:107], v[130:131], v[106:107], v[134:135]
	v_pk_fma_f32 v[102:103], v[132:133], v[102:103], v[136:137]
	v_cvt_pk_bf16_f32 v98, v98, v99
	v_cvt_pk_bf16_f32 v99, v100, v101
	v_cvt_pk_bf16_f32 v100, v106, v107
	s_nop 0
	v_cvt_pk_bf16_f32 v101, v102, v103
	global_store_dwordx4 v[104:105], v[98:101], off offset:256
	ds_read_b32 v98, v231 offset:4224
	v_pk_add_f32 v[102:103], v[92:93], v[162:163] op_sel_hi:[1,0]
	v_lshlrev_b64 v[100:101], 11, v[210:211]
	v_lshl_add_u64 v[100:101], v[100:101], 0, v[200:201]
	v_lshlrev_b64 v[100:101], 1, v[100:101]
	v_pk_add_f32 v[104:105], v[90:91], v[162:163] op_sel_hi:[1,0]
	v_cvt_pk_bf16_f32 v90, v94, v95
	v_cvt_pk_bf16_f32 v91, v96, v97
	v_lshl_add_u64 v[106:107], s[0:1], 0, v[100:101]
	v_cvt_pk_bf16_f32 v92, v104, v105
	v_cvt_pk_bf16_f32 v93, v102, v103
	global_store_dwordx4 v[106:107], v[90:93], off sc1
	s_waitcnt lgkmcnt(0)
	s_nop 0
	v_pk_mul_f32 v[90:91], v[94:95], v[98:99] op_sel_hi:[1,0]
	v_pk_mul_f32 v[92:93], v[96:97], v[98:99] op_sel_hi:[1,0]
	v_pk_mul_f32 v[94:95], v[104:105], v[98:99] op_sel_hi:[1,0]
	v_pk_fma_f32 v[92:93], v[160:161], v[92:93], v[156:157]
	v_pk_fma_f32 v[90:91], v[158:159], v[90:91], v[154:155]
	v_pk_mul_f32 v[96:97], v[102:103], v[98:99] op_sel_hi:[1,0]
	v_pk_fma_f32 v[94:95], v[146:147], v[94:95], v[150:151]
	v_pk_fma_f32 v[96:97], v[148:149], v[96:97], v[152:153]
	v_cvt_pk_bf16_f32 v90, v90, v91
	v_cvt_pk_bf16_f32 v91, v92, v93
	v_cvt_pk_bf16_f32 v92, v94, v95
	v_lshl_add_u64 v[94:95], s[94:95], 0, v[100:101]
	v_cvt_pk_bf16_f32 v93, v96, v97
	global_store_dwordx4 v[94:95], v[90:93], off
	s_nop 1
	v_pk_add_f32 v[90:91], v[84:85], v[162:163] op_sel_hi:[1,0]
	v_pk_add_f32 v[92:93], v[82:83], v[162:163] op_sel_hi:[1,0]
	v_cvt_pk_bf16_f32 v82, v86, v87
	v_cvt_pk_bf16_f32 v83, v88, v89
	s_nop 0
	v_cvt_pk_bf16_f32 v84, v92, v93
	v_cvt_pk_bf16_f32 v85, v90, v91
	global_store_dwordx4 v[106:107], v[82:85], off offset:256 sc1
	s_nop 1
	v_pk_mul_f32 v[82:83], v[86:87], v[98:99] op_sel_hi:[1,0]
	v_pk_mul_f32 v[84:85], v[88:89], v[98:99] op_sel_hi:[1,0]
	v_pk_fma_f32 v[82:83], v[138:139], v[82:83], v[142:143]
	v_pk_fma_f32 v[84:85], v[140:141], v[84:85], v[144:145]
	v_pk_mul_f32 v[86:87], v[92:93], v[98:99] op_sel_hi:[1,0]
	v_pk_mul_f32 v[88:89], v[90:91], v[98:99] op_sel_hi:[1,0]
	v_pk_fma_f32 v[86:87], v[130:131], v[86:87], v[134:135]
	v_pk_fma_f32 v[88:89], v[132:133], v[88:89], v[136:137]
	v_cvt_pk_bf16_f32 v82, v82, v83
	v_cvt_pk_bf16_f32 v83, v84, v85
	v_cvt_pk_bf16_f32 v84, v86, v87
	v_pk_add_f32 v[86:87], v[76:77], v[162:163] op_sel_hi:[1,0]
	v_cvt_pk_bf16_f32 v85, v88, v89
	global_store_dwordx4 v[94:95], v[82:85], off offset:256
	ds_read_b32 v82, v231 offset:4288
	v_pk_add_f32 v[88:89], v[74:75], v[162:163] op_sel_hi:[1,0]
	v_lshlrev_b64 v[84:85], 11, v[212:213]
	v_lshl_add_u64 v[84:85], v[84:85], 0, v[200:201]
	v_lshlrev_b64 v[84:85], 1, v[84:85]
	v_cvt_pk_bf16_f32 v74, v78, v79
	v_cvt_pk_bf16_f32 v75, v80, v81
	v_cvt_pk_bf16_f32 v76, v88, v89
	v_cvt_pk_bf16_f32 v77, v86, v87
	v_lshl_add_u64 v[90:91], s[0:1], 0, v[84:85]
	global_store_dwordx4 v[90:91], v[74:77], off sc1
	s_waitcnt lgkmcnt(0)
; __device__ __forceinline__ unsigned cvt_pk_bf16(float lo, float hi) { unsigned r; asm volatile("v_cvt_pk_bf16_f32 %0, %1, %2" : "=v"(r) : "v"(lo), "v"(hi)); return r; }
;     __device__ __forceinline__ void fused(f32x4 (&acc)[2][2][4][2], const Unit& u, int wr, int wc, int fr, int fq, PG8_LAS unsigned char* lds, int wid, int lane) const {
;     ...
; #pragma unroll
;         for (int ai = 0; ai < 2; ++ai)
; #pragma unroll
;             for (int m = 0; m < 4; ++m) { const int r = ai * HALF + wr * 64 + m * 16 + fr; const float rs = write_h ? S[r] : 0.0f; const size_t off = (size_t)(u.pm * BM + r) * 2048 + col0;
; #pragma unroll
;                 for (int bj = 0; bj < 2; ++bj) { const f32x4 x0 = acc[ai][bj][m][0] + poison, x1 = acc[ai][bj][m][1] + poison;
;                     if (out) { if (wofs == 0) { *(f32x4*)(out + off + bj * HALF) = x0; *(f32x4*)(out + off + bj * HALF + 4) = x1; } }
;                     else { u32x4 w; w.x = cvt_pk_bf16(x0[0], x0[1]); w.y = cvt_pk_bf16(x0[2], x0[3]); w.z = cvt_pk_bf16(x1[0], x1[1]); w.w = cvt_pk_bf16(x1[2], x1[3]); if (NT_FX) __builtin_nontemporal_store(w, (u32x4*)(X + wofs + off + bj * HALF)); else *(u32x4*)(X + wofs + off + bj * HALF) = w; }
;                     if (write_h) { const f32x4 h0 = x0 * rs * vs[bj][0] + vh[bj][0], h1 = x1 * rs * vs[bj][1] + vh[bj][1];
;                         u32x4 w; w.x = cvt_pk_bf16(h0[0], h0[1]); w.y = cvt_pk_bf16(h0[2], h0[3]); w.z = cvt_pk_bf16(h1[0], h1[1]); w.w = cvt_pk_bf16(h1[2], h1[3]); if (NT_FH) __builtin_nontemporal_store(w, (u32x4*)(H + wofs + off + bj * HALF)); else *(u32x4*)(H + wofs + off + bj * HALF) = w; } }
;                 asm volatile("" ::: "memory"); }
	s_nop 0
	v_pk_mul_f32 v[74:75], v[78:79], v[82:83] op_sel_hi:[1,0]
	v_pk_mul_f32 v[76:77], v[80:81], v[82:83] op_sel_hi:[1,0]
	v_pk_mul_f32 v[78:79], v[88:89], v[82:83] op_sel_hi:[1,0]
	v_pk_fma_f32 v[76:77], v[160:161], v[76:77], v[156:157]
	v_pk_fma_f32 v[74:75], v[158:159], v[74:75], v[154:155]
	v_pk_mul_f32 v[80:81], v[86:87], v[82:83] op_sel_hi:[1,0]
	v_pk_fma_f32 v[78:79], v[146:147], v[78:79], v[150:151]
	v_pk_fma_f32 v[80:81], v[148:149], v[80:81], v[152:153]
	v_cvt_pk_bf16_f32 v74, v74, v75
	v_cvt_pk_bf16_f32 v75, v76, v77
	v_cvt_pk_bf16_f32 v76, v78, v79
	v_lshl_add_u64 v[78:79], s[94:95], 0, v[84:85]
	v_cvt_pk_bf16_f32 v77, v80, v81
	global_store_dwordx4 v[78:79], v[74:77], off
	s_nop 1
	v_pk_add_f32 v[74:75], v[68:69], v[162:163] op_sel_hi:[1,0]
	v_pk_add_f32 v[76:77], v[66:67], v[162:163] op_sel_hi:[1,0]
	v_cvt_pk_bf16_f32 v66, v70, v71
	v_cvt_pk_bf16_f32 v67, v72, v73
	s_nop 0
	v_cvt_pk_bf16_f32 v68, v76, v77
	v_cvt_pk_bf16_f32 v69, v74, v75
	global_store_dwordx4 v[90:91], v[66:69], off offset:256 sc1
	s_nop 1
	v_pk_mul_f32 v[66:67], v[70:71], v[82:83] op_sel_hi:[1,0]
	v_pk_mul_f32 v[68:69], v[72:73], v[82:83] op_sel_hi:[1,0]
	v_pk_fma_f32 v[66:67], v[138:139], v[66:67], v[142:143]
	v_pk_fma_f32 v[68:69], v[140:141], v[68:69], v[144:145]
	v_pk_mul_f32 v[70:71], v[76:77], v[82:83] op_sel_hi:[1,0]
	v_pk_mul_f32 v[72:73], v[74:75], v[82:83] op_sel_hi:[1,0]
	v_pk_fma_f32 v[70:71], v[130:131], v[70:71], v[134:135]
	v_pk_fma_f32 v[72:73], v[132:133], v[72:73], v[136:137]
	v_cvt_pk_bf16_f32 v66, v66, v67
	v_cvt_pk_bf16_f32 v67, v68, v69
	v_cvt_pk_bf16_f32 v68, v70, v71
	v_pk_add_f32 v[70:71], v[60:61], v[162:163] op_sel_hi:[1,0]
	v_cvt_pk_bf16_f32 v69, v72, v73
	global_store_dwordx4 v[78:79], v[66:69], off offset:256
	ds_read_b32 v66, v231 offset:4608
	v_pk_add_f32 v[72:73], v[58:59], v[162:163] op_sel_hi:[1,0]
	v_lshlrev_b64 v[68:69], 11, v[190:191]
	v_lshl_add_u64 v[68:69], v[68:69], 0, v[200:201]
	v_lshlrev_b64 v[68:69], 1, v[68:69]
	v_cvt_pk_bf16_f32 v58, v62, v63
	v_cvt_pk_bf16_f32 v59, v64, v65
	v_cvt_pk_bf16_f32 v60, v72, v73
	v_cvt_pk_bf16_f32 v61, v70, v71
	v_lshl_add_u64 v[74:75], s[0:1], 0, v[68:69]
	global_store_dwordx4 v[74:75], v[58:61], off sc1
	s_waitcnt lgkmcnt(0)
	s_nop 0
	v_pk_mul_f32 v[58:59], v[62:63], v[66:67] op_sel_hi:[1,0]
	v_pk_mul_f32 v[60:61], v[64:65], v[66:67] op_sel_hi:[1,0]
	v_pk_mul_f32 v[62:63], v[72:73], v[66:67] op_sel_hi:[1,0]
	v_pk_fma_f32 v[60:61], v[160:161], v[60:61], v[156:157]
	v_pk_fma_f32 v[58:59], v[158:159], v[58:59], v[154:155]
	v_pk_mul_f32 v[64:65], v[70:71], v[66:67] op_sel_hi:[1,0]
	v_pk_fma_f32 v[62:63], v[146:147], v[62:63], v[150:151]
	v_pk_fma_f32 v[64:65], v[148:149], v[64:65], v[152:153]
	v_cvt_pk_bf16_f32 v58, v58, v59
	v_cvt_pk_bf16_f32 v59, v60, v61
	v_cvt_pk_bf16_f32 v60, v62, v63
	v_lshl_add_u64 v[62:63], s[94:95], 0, v[68:69]
	v_cvt_pk_bf16_f32 v61, v64, v65
	global_store_dwordx4 v[62:63], v[58:61], off
	s_nop 1
	v_pk_add_f32 v[58:59], v[52:53], v[162:163] op_sel_hi:[1,0]
	v_pk_add_f32 v[60:61], v[50:51], v[162:163] op_sel_hi:[1,0]
	v_cvt_pk_bf16_f32 v50, v54, v55
	v_cvt_pk_bf16_f32 v51, v56, v57
	s_nop 0
	v_cvt_pk_bf16_f32 v52, v60, v61
	v_cvt_pk_bf16_f32 v53, v58, v59
	global_store_dwordx4 v[74:75], v[50:53], off offset:256 sc1
	s_nop 1
	v_pk_mul_f32 v[50:51], v[54:55], v[66:67] op_sel_hi:[1,0]
	v_pk_mul_f32 v[52:53], v[56:57], v[66:67] op_sel_hi:[1,0]
	v_pk_fma_f32 v[50:51], v[138:139], v[50:51], v[142:143]
	v_pk_fma_f32 v[52:53], v[140:141], v[52:53], v[144:145]
	v_pk_mul_f32 v[54:55], v[60:61], v[66:67] op_sel_hi:[1,0]
	v_pk_mul_f32 v[56:57], v[58:59], v[66:67] op_sel_hi:[1,0]
	v_pk_fma_f32 v[54:55], v[130:131], v[54:55], v[134:135]
	v_pk_fma_f32 v[56:57], v[132:133], v[56:57], v[136:137]
	v_cvt_pk_bf16_f32 v50, v50, v51
	v_cvt_pk_bf16_f32 v51, v52, v53
	v_cvt_pk_bf16_f32 v52, v54, v55
	v_pk_add_f32 v[54:55], v[44:45], v[162:163] op_sel_hi:[1,0]
	v_cvt_pk_bf16_f32 v53, v56, v57
	global_store_dwordx4 v[62:63], v[50:53], off offset:256
	ds_read_b32 v50, v231 offset:4672
	v_pk_add_f32 v[56:57], v[42:43], v[162:163] op_sel_hi:[1,0]
	v_lshlrev_b64 v[52:53], 11, v[182:183]
	v_lshl_add_u64 v[52:53], v[52:53], 0, v[200:201]
	v_lshlrev_b64 v[52:53], 1, v[52:53]
	v_cvt_pk_bf16_f32 v42, v46, v47
	v_cvt_pk_bf16_f32 v43, v48, v49
	v_cvt_pk_bf16_f32 v44, v56, v57
	v_cvt_pk_bf16_f32 v45, v54, v55
	v_lshl_add_u64 v[58:59], s[0:1], 0, v[52:53]
	global_store_dwordx4 v[58:59], v[42:45], off sc1
	s_waitcnt lgkmcnt(0)
	s_nop 0
	v_pk_mul_f32 v[42:43], v[46:47], v[50:51] op_sel_hi:[1,0]
	v_pk_mul_f32 v[44:45], v[48:49], v[50:51] op_sel_hi:[1,0]
	v_pk_mul_f32 v[46:47], v[56:57], v[50:51] op_sel_hi:[1,0]
	v_pk_fma_f32 v[44:45], v[160:161], v[44:45], v[156:157]
	v_pk_fma_f32 v[42:43], v[158:159], v[42:43], v[154:155]
	v_pk_mul_f32 v[48:49], v[54:55], v[50:51] op_sel_hi:[1,0]
	v_pk_fma_f32 v[46:47], v[146:147], v[46:47], v[150:151]
	v_pk_fma_f32 v[48:49], v[148:149], v[48:49], v[152:153]
	v_cvt_pk_bf16_f32 v42, v42, v43
	v_cvt_pk_bf16_f32 v43, v44, v45
	v_cvt_pk_bf16_f32 v44, v46, v47
	v_lshl_add_u64 v[46:47], s[94:95], 0, v[52:53]
	v_cvt_pk_bf16_f32 v45, v48, v49
	global_store_dwordx4 v[46:47], v[42:45], off
	s_nop 1
	v_pk_add_f32 v[42:43], v[36:37], v[162:163] op_sel_hi:[1,0]
	v_pk_add_f32 v[44:45], v[34:35], v[162:163] op_sel_hi:[1,0]
	v_cvt_pk_bf16_f32 v34, v38, v39
	v_cvt_pk_bf16_f32 v35, v40, v41
	s_nop 0
	v_cvt_pk_bf16_f32 v36, v44, v45
	v_cvt_pk_bf16_f32 v37, v42, v43
	global_store_dwordx4 v[58:59], v[34:37], off offset:256 sc1
	s_nop 1
	v_pk_mul_f32 v[34:35], v[38:39], v[50:51] op_sel_hi:[1,0]
	v_pk_mul_f32 v[36:37], v[40:41], v[50:51] op_sel_hi:[1,0]
	v_pk_fma_f32 v[34:35], v[138:139], v[34:35], v[142:143]
	v_pk_fma_f32 v[36:37], v[140:141], v[36:37], v[144:145]
	v_pk_mul_f32 v[38:39], v[44:45], v[50:51] op_sel_hi:[1,0]
	v_pk_mul_f32 v[40:41], v[42:43], v[50:51] op_sel_hi:[1,0]
	v_pk_fma_f32 v[38:39], v[130:131], v[38:39], v[134:135]
	v_pk_fma_f32 v[40:41], v[132:133], v[40:41], v[136:137]
	v_cvt_pk_bf16_f32 v34, v34, v35
	v_cvt_pk_bf16_f32 v35, v36, v37
	v_cvt_pk_bf16_f32 v36, v38, v39
	v_pk_add_f32 v[38:39], v[28:29], v[162:163] op_sel_hi:[1,0]
	v_cvt_pk_bf16_f32 v37, v40, v41
	global_store_dwordx4 v[46:47], v[34:37], off offset:256
	ds_read_b32 v34, v231 offset:4736
	v_pk_add_f32 v[40:41], v[26:27], v[162:163] op_sel_hi:[1,0]
	v_lshlrev_b64 v[36:37], 11, v[174:175]
	v_lshl_add_u64 v[36:37], v[36:37], 0, v[200:201]
	v_lshlrev_b64 v[36:37], 1, v[36:37]
	v_cvt_pk_bf16_f32 v26, v30, v31
	v_cvt_pk_bf16_f32 v27, v32, v33
	v_cvt_pk_bf16_f32 v28, v40, v41
	v_cvt_pk_bf16_f32 v29, v38, v39
	v_lshl_add_u64 v[42:43], s[0:1], 0, v[36:37]
	global_store_dwordx4 v[42:43], v[26:29], off sc1
	s_waitcnt lgkmcnt(0)
; __device__ __forceinline__ unsigned cvt_pk_bf16(float lo, float hi) { unsigned r; asm volatile("v_cvt_pk_bf16_f32 %0, %1, %2" : "=v"(r) : "v"(lo), "v"(hi)); return r; }
;     __device__ __forceinline__ void fused(f32x4 (&acc)[2][2][4][2], const Unit& u, int wr, int wc, int fr, int fq, PG8_LAS unsigned char* lds, int wid, int lane) const {
;     ...
; #pragma unroll
;         for (int ai = 0; ai < 2; ++ai)
; #pragma unroll
;             for (int m = 0; m < 4; ++m) { const int r = ai * HALF + wr * 64 + m * 16 + fr; const float rs = write_h ? S[r] : 0.0f; const size_t off = (size_t)(u.pm * BM + r) * 2048 + col0;
; #pragma unroll
;                 for (int bj = 0; bj < 2; ++bj) { const f32x4 x0 = acc[ai][bj][m][0] + poison, x1 = acc[ai][bj][m][1] + poison;
;                     if (out) { if (wofs == 0) { *(f32x4*)(out + off + bj * HALF) = x0; *(f32x4*)(out + off + bj * HALF + 4) = x1; } }
;                     else { u32x4 w; w.x = cvt_pk_bf16(x0[0], x0[1]); w.y = cvt_pk_bf16(x0[2], x0[3]); w.z = cvt_pk_bf16(x1[0], x1[1]); w.w = cvt_pk_bf16(x1[2], x1[3]); if (NT_FX) __builtin_nontemporal_store(w, (u32x4*)(X + wofs + off + bj * HALF)); else *(u32x4*)(X + wofs + off + bj * HALF) = w; }
;                     if (write_h) { const f32x4 h0 = x0 * rs * vs[bj][0] + vh[bj][0], h1 = x1 * rs * vs[bj][1] + vh[bj][1];
;                         u32x4 w; w.x = cvt_pk_bf16(h0[0], h0[1]); w.y = cvt_pk_bf16(h0[2], h0[3]); w.z = cvt_pk_bf16(h1[0], h1[1]); w.w = cvt_pk_bf16(h1[2], h1[3]); if (NT_FH) __builtin_nontemporal_store(w, (u32x4*)(H + wofs + off + bj * HALF)); else *(u32x4*)(H + wofs + off + bj * HALF) = w; } }
;                 asm volatile("" ::: "memory"); }
; __device__ __forceinline__ void xcd_barrier(const XcdBarrier& b) {
;     asm volatile("s_waitcnt vmcnt(0)" ::: "memory");
;     __syncthreads();
;     if (threadIdx.x == 0) {
;         unsigned* bar = b.bar;
;         __builtin_amdgcn_s_waitcnt(0);
;         unsigned nloc = b.st[0], nx = b.st[1];
;         if (nloc == 0u) { xcd_barrier_complete(bar, b.x, nloc, nx); b.st[0] = nloc; b.st[1] = nx; }
	s_nop 0
	v_pk_mul_f32 v[26:27], v[30:31], v[34:35] op_sel_hi:[1,0]
	v_pk_mul_f32 v[28:29], v[32:33], v[34:35] op_sel_hi:[1,0]
	v_pk_mul_f32 v[30:31], v[40:41], v[34:35] op_sel_hi:[1,0]
	v_pk_fma_f32 v[28:29], v[160:161], v[28:29], v[156:157]
	v_pk_fma_f32 v[26:27], v[158:159], v[26:27], v[154:155]
	v_pk_mul_f32 v[32:33], v[38:39], v[34:35] op_sel_hi:[1,0]
	v_pk_fma_f32 v[30:31], v[146:147], v[30:31], v[150:151]
	v_pk_fma_f32 v[32:33], v[148:149], v[32:33], v[152:153]
	v_cvt_pk_bf16_f32 v26, v26, v27
	v_cvt_pk_bf16_f32 v27, v28, v29
	v_cvt_pk_bf16_f32 v28, v30, v31
	v_lshl_add_u64 v[30:31], s[94:95], 0, v[36:37]
	v_cvt_pk_bf16_f32 v29, v32, v33
	global_store_dwordx4 v[30:31], v[26:29], off
	s_nop 1
	v_pk_add_f32 v[26:27], v[20:21], v[162:163] op_sel_hi:[1,0]
	v_pk_add_f32 v[28:29], v[18:19], v[162:163] op_sel_hi:[1,0]
	v_cvt_pk_bf16_f32 v18, v22, v23
	v_cvt_pk_bf16_f32 v19, v24, v25
	s_nop 0
	v_cvt_pk_bf16_f32 v20, v28, v29
	v_cvt_pk_bf16_f32 v21, v26, v27
	global_store_dwordx4 v[42:43], v[18:21], off offset:256 sc1
	s_nop 1
	v_pk_mul_f32 v[18:19], v[22:23], v[34:35] op_sel_hi:[1,0]
	v_pk_mul_f32 v[20:21], v[24:25], v[34:35] op_sel_hi:[1,0]
	v_pk_fma_f32 v[18:19], v[138:139], v[18:19], v[142:143]
	v_pk_fma_f32 v[20:21], v[140:141], v[20:21], v[144:145]
	v_pk_mul_f32 v[22:23], v[28:29], v[34:35] op_sel_hi:[1,0]
	v_pk_mul_f32 v[24:25], v[26:27], v[34:35] op_sel_hi:[1,0]
	v_pk_fma_f32 v[22:23], v[130:131], v[22:23], v[134:135]
	v_pk_fma_f32 v[24:25], v[132:133], v[24:25], v[136:137]
	v_cvt_pk_bf16_f32 v18, v18, v19
	v_cvt_pk_bf16_f32 v19, v20, v21
	v_cvt_pk_bf16_f32 v20, v22, v23
	v_pk_add_f32 v[22:23], v[12:13], v[162:163] op_sel_hi:[1,0]
	v_cvt_pk_bf16_f32 v21, v24, v25
	global_store_dwordx4 v[30:31], v[18:21], off offset:256
	ds_read_b32 v18, v231 offset:4800
	v_pk_add_f32 v[24:25], v[10:11], v[162:163] op_sel_hi:[1,0]
	v_lshlrev_b64 v[20:21], 11, v[166:167]
	v_lshl_add_u64 v[20:21], v[20:21], 0, v[200:201]
	v_lshlrev_b64 v[20:21], 1, v[20:21]
	v_cvt_pk_bf16_f32 v10, v14, v15
	v_cvt_pk_bf16_f32 v11, v16, v17
	v_cvt_pk_bf16_f32 v12, v24, v25
	v_cvt_pk_bf16_f32 v13, v22, v23
	v_lshl_add_u64 v[26:27], s[0:1], 0, v[20:21]
	global_store_dwordx4 v[26:27], v[10:13], off sc1
	s_waitcnt lgkmcnt(0)
	s_nop 0
	v_pk_mul_f32 v[10:11], v[14:15], v[18:19] op_sel_hi:[1,0]
	v_pk_mul_f32 v[12:13], v[16:17], v[18:19] op_sel_hi:[1,0]
	v_pk_mul_f32 v[14:15], v[24:25], v[18:19] op_sel_hi:[1,0]
	v_pk_fma_f32 v[12:13], v[160:161], v[12:13], v[156:157]
	v_pk_fma_f32 v[10:11], v[158:159], v[10:11], v[154:155]
	v_pk_mul_f32 v[16:17], v[22:23], v[18:19] op_sel_hi:[1,0]
	v_pk_fma_f32 v[14:15], v[146:147], v[14:15], v[150:151]
	v_pk_fma_f32 v[16:17], v[148:149], v[16:17], v[152:153]
	v_cvt_pk_bf16_f32 v10, v10, v11
	v_cvt_pk_bf16_f32 v11, v12, v13
	v_cvt_pk_bf16_f32 v12, v14, v15
	v_lshl_add_u64 v[14:15], s[94:95], 0, v[20:21]
	v_cvt_pk_bf16_f32 v13, v16, v17
	global_store_dwordx4 v[14:15], v[10:13], off
	s_nop 1
	v_pk_add_f32 v[10:11], v[4:5], v[162:163] op_sel_hi:[1,0]
	v_pk_add_f32 v[12:13], v[2:3], v[162:163] op_sel_hi:[1,0]
	v_cvt_pk_bf16_f32 v2, v6, v7
	v_cvt_pk_bf16_f32 v3, v8, v9
	s_nop 0
	v_cvt_pk_bf16_f32 v4, v12, v13
	v_cvt_pk_bf16_f32 v5, v10, v11
	global_store_dwordx4 v[26:27], v[2:5], off offset:256 sc1
	s_nop 1
	v_pk_mul_f32 v[2:3], v[6:7], v[18:19] op_sel_hi:[1,0]
	v_pk_mul_f32 v[4:5], v[8:9], v[18:19] op_sel_hi:[1,0]
	v_pk_fma_f32 v[2:3], v[138:139], v[2:3], v[142:143]
	v_pk_fma_f32 v[4:5], v[140:141], v[4:5], v[144:145]
	v_pk_mul_f32 v[6:7], v[12:13], v[18:19] op_sel_hi:[1,0]
	v_pk_mul_f32 v[8:9], v[10:11], v[18:19] op_sel_hi:[1,0]
	v_pk_fma_f32 v[6:7], v[130:131], v[6:7], v[134:135]
	v_pk_fma_f32 v[8:9], v[132:133], v[8:9], v[136:137]
	v_cvt_pk_bf16_f32 v2, v2, v3
	v_cvt_pk_bf16_f32 v3, v4, v5
	v_cvt_pk_bf16_f32 v4, v6, v7
	s_nop 0
	v_cvt_pk_bf16_f32 v5, v8, v9
	global_store_dwordx4 v[14:15], v[2:5], off offset:256
	s_cbranch_scc1 .LBB0_1027
	s_waitcnt vmcnt(0)
	s_barrier
	s_and_saveexec_b64 s[0:1], s[92:93]
	s_cbranch_execz .LBB0_1026
	v_readlane_b32 s4, v254, 5
	s_waitcnt vmcnt(0) expcnt(0) lgkmcnt(0)
	s_nop 0
	v_mov_b32_e32 v2, s4
	ds_read_b32 v4, v2
	v_readlane_b32 s4, v254, 6
	s_waitcnt lgkmcnt(0)
	v_cmp_ne_u32_e32 vcc, 0, v4
	v_mov_b32_e32 v2, s4
	ds_read_b32 v2, v2
	s_cbranch_vccnz .LBB0_990
	v_readlane_b32 s6, v250, 0
	v_readlane_b32 s7, v250, 1
	s_load_dwordx2 s[4:5], s[6:7], 0x4
	s_mov_b32 s11, 1
	s_waitcnt lgkmcnt(0)
	s_mul_i32 s10, s4, s33
	s_mul_i32 s10, s10, s5
	s_branch .LBB0_978

; __device__ __forceinline__ unsigned cvt_pk_bf16(float lo, float hi) { unsigned r; asm volatile("v_cvt_pk_bf16_f32 %0, %1, %2" : "=v"(r) : "v"(lo), "v"(hi)); return r; }
;     __device__ __forceinline__ void fused(f32x4 (&acc)[2][2][4][2], const Unit& u, int wr, int wc, int fr, int fq, PG8_LAS unsigned char* lds, int wid, int lane) const {
;     ...
;         const float poison = bad ? __builtin_nanf("") : 0.0f;
;         f32x4 vs[2][2], vh[2][2];
; #pragma unroll
;         for (int bj = 0; bj < 2; ++bj)
; #pragma unroll
;             for (int n = 0; n < 2; ++n) { vs[bj][n] = write_h ? *(const f32x4*)(cb + 2048 + bj * HALF + 4 * n) : (f32x4){0.f, 0.f, 0.f, 0.f}; vh[bj][n] = write_h ? *(const f32x4*)(cb + 4096 + bj * HALF + 4 * n) : (f32x4){0.f, 0.f, 0.f, 0.f}; }
; #pragma unroll
;         for (int ai = 0; ai < 2; ++ai)
; #pragma unroll
;             for (int m = 0; m < 4; ++m) { const int r = ai * HALF + wr * 64 + m * 16 + fr; const float rs = write_h ? S[r] : 0.0f; const size_t off = (size_t)(u.pm * BM + r) * 2048 + col0;
; #pragma unroll
;                 for (int bj = 0; bj < 2; ++bj) { const f32x4 x0 = acc[ai][bj][m][0] + poison, x1 = acc[ai][bj][m][1] + poison;
;                     if (out) { if (wofs == 0) { *(f32x4*)(out + off + bj * HALF) = x0; *(f32x4*)(out + off + bj * HALF + 4) = x1; } }
;                     else { u32x4 w; w.x = cvt_pk_bf16(x0[0], x0[1]); w.y = cvt_pk_bf16(x0[2], x0[3]); w.z = cvt_pk_bf16(x1[0], x1[1]); w.w = cvt_pk_bf16(x1[2], x1[3]); if (NT_FX) __builtin_nontemporal_store(w, (u32x4*)(X + wofs + off + bj * HALF)); else *(u32x4*)(X + wofs + off + bj * HALF) = w; }
;                     if (write_h) { const f32x4 h0 = x0 * rs * vs[bj][0] + vh[bj][0], h1 = x1 * rs * vs[bj][1] + vh[bj][1];
;                         u32x4 w; w.x = cvt_pk_bf16(h0[0], h0[1]); w.y = cvt_pk_bf16(h0[2], h0[3]); w.z = cvt_pk_bf16(h1[0], h1[1]); w.w = cvt_pk_bf16(h1[2], h1[3]); if (NT_FH) __builtin_nontemporal_store(w, (u32x4*)(H + wofs + off + bj * HALF)); else *(u32x4*)(H + wofs + off + bj * HALF) = w; } }
;                 asm volatile("" ::: "memory"); }
.LBB0_1884:
	s_or_b64 exec, exec, s[0:1]
	s_mov_b64 s[0:1], 0x2000
	s_waitcnt lgkmcnt(1)
	v_lshl_add_u64 v[130:131], v[182:183], 0, s[0:1]
	s_mov_b64 s[0:1], 0x4000
	v_lshl_add_u64 v[132:133], v[182:183], 0, s[0:1]
	s_movk_i32 s0, 0x2000
	v_add_co_u32_e32 v134, vcc, s0, v182
	s_waitcnt lgkmcnt(0)
	s_barrier
	s_nop 0
	v_addc_co_u32_e32 v135, vcc, 0, v183, vcc
	s_movk_i32 s0, 0x4000
	global_load_dwordx4 v[146:149], v[134:135], off
	v_add_co_u32_e32 v136, vcc, s0, v182
	s_mov_b64 s[0:1], 0x2200
	v_lshl_add_u64 v[138:139], v[182:183], 0, s[0:1]
	s_mov_b64 s[0:1], 0x4200
	v_addc_co_u32_e32 v137, vcc, 0, v183, vcc
	v_lshl_add_u64 v[142:143], v[182:183], 0, s[0:1]
	global_load_dwordx4 v[150:153], v[136:137], off
	global_load_dwordx4 v[154:157], v[130:131], off offset:16
	global_load_dwordx4 v[158:161], v[132:133], off offset:16
	s_nop 0
	global_load_dwordx4 v[130:133], v[134:135], off offset:512
	s_nop 0
	global_load_dwordx4 v[134:137], v[136:137], off offset:512
	s_nop 0
	global_load_dwordx4 v[138:141], v[138:139], off offset:16
	s_nop 0
	global_load_dwordx4 v[142:145], v[142:143], off offset:16
	ds_read_b32 v184, v188 offset:4096
	v_add_u32_e32 v176, s18, v186
	s_waitcnt lgkmcnt(1)
	v_or_b32_e32 v162, v162, v192
	v_ashrrev_i32_e32 v177, 31, v176
	v_cmp_eq_u32_e32 vcc, 0, v162
	v_mov_b32_e32 v162, 0x7fc00000
	v_add_u32_e32 v164, 0xb0, v176
	v_add_u32_e32 v166, 0xa0, v176
	v_add_u32_e32 v168, 0x90, v176
	v_add_u32_e32 v170, 0x80, v176
	v_add_u32_e32 v172, 48, v176
	v_add_u32_e32 v174, 32, v176
	v_add_u32_e32 v182, 16, v176
	v_cndmask_b32_e64 v162, v162, 0, vcc
	v_lshlrev_b64 v[186:187], 11, v[176:177]
	v_lshlrev_b64 v[176:177], 12, v[176:177]
	v_pk_add_f32 v[124:125], v[124:125], v[162:163] op_sel_hi:[1,0]
	v_pk_add_f32 v[122:123], v[122:123], v[162:163] op_sel_hi:[1,0]
	v_pk_add_f32 v[128:129], v[128:129], v[162:163] op_sel_hi:[1,0]
	v_pk_add_f32 v[126:127], v[126:127], v[162:163] op_sel_hi:[1,0]
	v_pk_add_f32 v[190:191], v[116:117], v[162:163] op_sel_hi:[1,0]
	v_pk_add_f32 v[192:193], v[114:115], v[162:163] op_sel_hi:[1,0]
	v_cvt_pk_bf16_f32 v114, v122, v123
	v_cvt_pk_bf16_f32 v115, v124, v125
	v_cvt_pk_bf16_f32 v116, v126, v127
	v_cvt_pk_bf16_f32 v117, v128, v129
	v_lshl_add_u64 v[176:177], v[178:179], 0, v[176:177]
	global_store_dwordx4 v[176:177], v[114:117], off sc1
	v_lshl_add_u64 v[186:187], v[186:187], 0, v[180:181]
	v_lshl_add_u64 v[186:187], v[186:187], 1, s[94:95]
	s_waitcnt lgkmcnt(0)
	v_pk_mul_f32 v[114:115], v[122:123], v[184:185] op_sel_hi:[1,0]
	v_pk_mul_f32 v[116:117], v[124:125], v[184:185] op_sel_hi:[1,0]
	v_pk_mul_f32 v[122:123], v[126:127], v[184:185] op_sel_hi:[1,0]
	v_pk_mul_f32 v[124:125], v[128:129], v[184:185] op_sel_hi:[1,0]
	v_pk_add_f32 v[120:121], v[120:121], v[162:163] op_sel_hi:[1,0]
	v_pk_add_f32 v[118:119], v[118:119], v[162:163] op_sel_hi:[1,0]
	v_pk_mul_f32 v[200:201], v[192:193], v[184:185] op_sel_hi:[1,0]
	v_pk_mul_f32 v[126:127], v[118:119], v[184:185] op_sel_hi:[1,0]
	v_pk_mul_f32 v[128:129], v[120:121], v[184:185] op_sel_hi:[1,0]
	v_pk_mul_f32 v[184:185], v[190:191], v[184:185] op_sel_hi:[1,0]
	v_ashrrev_i32_e32 v183, 31, v182
	v_pk_add_f32 v[112:113], v[112:113], v[162:163] op_sel_hi:[1,0]
	v_pk_add_f32 v[110:111], v[110:111], v[162:163] op_sel_hi:[1,0]
	v_pk_add_f32 v[104:105], v[104:105], v[162:163] op_sel_hi:[1,0]
	v_pk_add_f32 v[102:103], v[102:103], v[162:163] op_sel_hi:[1,0]
	v_ashrrev_i32_e32 v175, 31, v174
	v_pk_add_f32 v[96:97], v[96:97], v[162:163] op_sel_hi:[1,0]
	v_pk_add_f32 v[94:95], v[94:95], v[162:163] op_sel_hi:[1,0]
	v_pk_add_f32 v[88:89], v[88:89], v[162:163] op_sel_hi:[1,0]
	v_pk_add_f32 v[86:87], v[86:87], v[162:163] op_sel_hi:[1,0]
	v_ashrrev_i32_e32 v173, 31, v172
	v_pk_add_f32 v[80:81], v[80:81], v[162:163] op_sel_hi:[1,0]
	v_pk_add_f32 v[78:79], v[78:79], v[162:163] op_sel_hi:[1,0]
	v_pk_add_f32 v[72:73], v[72:73], v[162:163] op_sel_hi:[1,0]
	v_pk_add_f32 v[70:71], v[70:71], v[162:163] op_sel_hi:[1,0]
	v_ashrrev_i32_e32 v171, 31, v170
	v_pk_add_f32 v[64:65], v[64:65], v[162:163] op_sel_hi:[1,0]
	v_pk_add_f32 v[62:63], v[62:63], v[162:163] op_sel_hi:[1,0]
	v_pk_add_f32 v[56:57], v[56:57], v[162:163] op_sel_hi:[1,0]
	v_pk_add_f32 v[54:55], v[54:55], v[162:163] op_sel_hi:[1,0]
	v_ashrrev_i32_e32 v169, 31, v168
	v_pk_add_f32 v[48:49], v[48:49], v[162:163] op_sel_hi:[1,0]
	v_pk_add_f32 v[46:47], v[46:47], v[162:163] op_sel_hi:[1,0]
	v_pk_add_f32 v[40:41], v[40:41], v[162:163] op_sel_hi:[1,0]
	v_pk_add_f32 v[38:39], v[38:39], v[162:163] op_sel_hi:[1,0]
	v_ashrrev_i32_e32 v167, 31, v166
	v_pk_add_f32 v[32:33], v[32:33], v[162:163] op_sel_hi:[1,0]
	v_pk_add_f32 v[30:31], v[30:31], v[162:163] op_sel_hi:[1,0]
	v_pk_add_f32 v[24:25], v[24:25], v[162:163] op_sel_hi:[1,0]
	v_pk_add_f32 v[22:23], v[22:23], v[162:163] op_sel_hi:[1,0]
	v_ashrrev_i32_e32 v165, 31, v164
	v_pk_add_f32 v[16:17], v[16:17], v[162:163] op_sel_hi:[1,0]
	v_pk_add_f32 v[14:15], v[14:15], v[162:163] op_sel_hi:[1,0]
	v_pk_add_f32 v[8:9], v[8:9], v[162:163] op_sel_hi:[1,0]
	s_waitcnt vmcnt(7)
	v_pk_fma_f32 v[116:117], v[148:149], v[116:117], v[152:153]
	v_pk_fma_f32 v[114:115], v[146:147], v[114:115], v[150:151]
	s_waitcnt vmcnt(5)
	v_pk_fma_f32 v[124:125], v[156:157], v[124:125], v[160:161]
	v_pk_fma_f32 v[122:123], v[154:155], v[122:123], v[158:159]
	v_cvt_pk_bf16_f32 v114, v114, v115
	v_cvt_pk_bf16_f32 v115, v116, v117
	s_waitcnt vmcnt(3)
	v_pk_fma_f32 v[128:129], v[132:133], v[128:129], v[136:137]
	v_cvt_pk_bf16_f32 v116, v122, v123
	v_cvt_pk_bf16_f32 v117, v124, v125
	global_store_dwordx4 v[186:187], v[114:117], off
	v_pk_fma_f32 v[126:127], v[130:131], v[126:127], v[134:135]
	v_lshlrev_b64 v[122:123], 12, v[182:183]
	v_cvt_pk_bf16_f32 v114, v118, v119
	v_cvt_pk_bf16_f32 v115, v120, v121
	v_cvt_pk_bf16_f32 v116, v192, v193
	v_cvt_pk_bf16_f32 v117, v190, v191
	global_store_dwordx4 v[176:177], v[114:117], off offset:256 sc1
	s_waitcnt vmcnt(3)
; __device__ __forceinline__ unsigned cvt_pk_bf16(float lo, float hi) { unsigned r; asm volatile("v_cvt_pk_bf16_f32 %0, %1, %2" : "=v"(r) : "v"(lo), "v"(hi)); return r; }
;     __device__ __forceinline__ void fused(f32x4 (&acc)[2][2][4][2], const Unit& u, int wr, int wc, int fr, int fq, PG8_LAS unsigned char* lds, int wid, int lane) const {
;     ...
; #pragma unroll
;         for (int ai = 0; ai < 2; ++ai)
; #pragma unroll
;             for (int m = 0; m < 4; ++m) { const int r = ai * HALF + wr * 64 + m * 16 + fr; const float rs = write_h ? S[r] : 0.0f; const size_t off = (size_t)(u.pm * BM + r) * 2048 + col0;
; #pragma unroll
;                 for (int bj = 0; bj < 2; ++bj) { const f32x4 x0 = acc[ai][bj][m][0] + poison, x1 = acc[ai][bj][m][1] + poison;
;                     if (out) { if (wofs == 0) { *(f32x4*)(out + off + bj * HALF) = x0; *(f32x4*)(out + off + bj * HALF + 4) = x1; } }
;                     else { u32x4 w; w.x = cvt_pk_bf16(x0[0], x0[1]); w.y = cvt_pk_bf16(x0[2], x0[3]); w.z = cvt_pk_bf16(x1[0], x1[1]); w.w = cvt_pk_bf16(x1[2], x1[3]); if (NT_FX) __builtin_nontemporal_store(w, (u32x4*)(X + wofs + off + bj * HALF)); else *(u32x4*)(X + wofs + off + bj * HALF) = w; }
;                     if (write_h) { const f32x4 h0 = x0 * rs * vs[bj][0] + vh[bj][0], h1 = x1 * rs * vs[bj][1] + vh[bj][1];
;                         u32x4 w; w.x = cvt_pk_bf16(h0[0], h0[1]); w.y = cvt_pk_bf16(h0[2], h0[3]); w.z = cvt_pk_bf16(h1[0], h1[1]); w.w = cvt_pk_bf16(h1[2], h1[3]); if (NT_FH) __builtin_nontemporal_store(w, (u32x4*)(H + wofs + off + bj * HALF)); else *(u32x4*)(H + wofs + off + bj * HALF) = w; } }
;                 asm volatile("" ::: "memory"); }
	v_pk_fma_f32 v[118:119], v[140:141], v[184:185], v[144:145]
	v_pk_add_f32 v[120:121], v[106:107], v[162:163] op_sel_hi:[1,0]
	v_pk_fma_f32 v[116:117], v[138:139], v[200:201], v[142:143]
	v_cvt_pk_bf16_f32 v114, v126, v127
	v_cvt_pk_bf16_f32 v115, v128, v129
	v_lshl_add_u64 v[122:123], v[178:179], 0, v[122:123]
	v_cvt_pk_bf16_f32 v116, v116, v117
	v_cvt_pk_bf16_f32 v117, v118, v119
	global_store_dwordx4 v[186:187], v[114:117], off offset:256
	ds_read_b32 v114, v188 offset:4160
	v_pk_add_f32 v[118:119], v[108:109], v[162:163] op_sel_hi:[1,0]
	v_cvt_pk_bf16_f32 v106, v110, v111
	v_cvt_pk_bf16_f32 v107, v112, v113
	v_cvt_pk_bf16_f32 v108, v120, v121
	v_lshlrev_b64 v[116:117], 11, v[182:183]
	v_cvt_pk_bf16_f32 v109, v118, v119
	global_store_dwordx4 v[122:123], v[106:109], off sc1
	v_lshl_add_u64 v[116:117], v[116:117], 0, v[180:181]
	v_pk_add_f32 v[6:7], v[6:7], v[162:163] op_sel_hi:[1,0]
	s_waitcnt lgkmcnt(0)
	v_pk_mul_f32 v[106:107], v[110:111], v[114:115] op_sel_hi:[1,0]
	v_pk_mul_f32 v[108:109], v[112:113], v[114:115] op_sel_hi:[1,0]
	v_pk_mul_f32 v[110:111], v[120:121], v[114:115] op_sel_hi:[1,0]
	v_pk_fma_f32 v[108:109], v[148:149], v[108:109], v[152:153]
	v_pk_fma_f32 v[106:107], v[146:147], v[106:107], v[150:151]
	v_pk_mul_f32 v[112:113], v[118:119], v[114:115] op_sel_hi:[1,0]
	v_pk_fma_f32 v[110:111], v[154:155], v[110:111], v[158:159]
	v_pk_fma_f32 v[112:113], v[156:157], v[112:113], v[160:161]
	v_cvt_pk_bf16_f32 v106, v106, v107
	v_cvt_pk_bf16_f32 v107, v108, v109
	v_cvt_pk_bf16_f32 v108, v110, v111
	v_lshl_add_u64 v[110:111], v[116:117], 1, s[94:95]
	v_cvt_pk_bf16_f32 v109, v112, v113
	global_store_dwordx4 v[110:111], v[106:109], off
	s_add_i32 s18, s81, 7
	s_cmp_ge_i32 s18, s83
	v_pk_add_f32 v[106:107], v[100:101], v[162:163] op_sel_hi:[1,0]
	v_pk_add_f32 v[108:109], v[98:99], v[162:163] op_sel_hi:[1,0]
	v_cvt_pk_bf16_f32 v98, v102, v103
	v_cvt_pk_bf16_f32 v99, v104, v105
	s_nop 0
	v_cvt_pk_bf16_f32 v100, v108, v109
	v_cvt_pk_bf16_f32 v101, v106, v107
	global_store_dwordx4 v[122:123], v[98:101], off offset:256 sc1
	s_nop 1
	v_pk_mul_f32 v[98:99], v[102:103], v[114:115] op_sel_hi:[1,0]
	v_pk_mul_f32 v[100:101], v[104:105], v[114:115] op_sel_hi:[1,0]
	v_pk_fma_f32 v[98:99], v[130:131], v[98:99], v[134:135]
	v_pk_fma_f32 v[100:101], v[132:133], v[100:101], v[136:137]
	v_pk_mul_f32 v[102:103], v[108:109], v[114:115] op_sel_hi:[1,0]
	v_pk_mul_f32 v[104:105], v[106:107], v[114:115] op_sel_hi:[1,0]
	v_pk_fma_f32 v[102:103], v[138:139], v[102:103], v[142:143]
	v_pk_fma_f32 v[104:105], v[140:141], v[104:105], v[144:145]
	v_cvt_pk_bf16_f32 v98, v98, v99
	v_cvt_pk_bf16_f32 v99, v100, v101
	v_cvt_pk_bf16_f32 v100, v102, v103
	v_lshlrev_b64 v[106:107], 12, v[174:175]
	v_cvt_pk_bf16_f32 v101, v104, v105
	global_store_dwordx4 v[110:111], v[98:101], off offset:256
	ds_read_b32 v98, v188 offset:4224
	v_pk_add_f32 v[102:103], v[92:93], v[162:163] op_sel_hi:[1,0]
	v_pk_add_f32 v[104:105], v[90:91], v[162:163] op_sel_hi:[1,0]
	v_cvt_pk_bf16_f32 v90, v94, v95
	v_cvt_pk_bf16_f32 v91, v96, v97
	v_lshl_add_u64 v[106:107], v[178:179], 0, v[106:107]
	v_cvt_pk_bf16_f32 v92, v104, v105
	v_cvt_pk_bf16_f32 v93, v102, v103
	v_lshlrev_b64 v[100:101], 11, v[174:175]
	global_store_dwordx4 v[106:107], v[90:93], off sc1
	v_lshl_add_u64 v[100:101], v[100:101], 0, v[180:181]
	s_waitcnt lgkmcnt(0)
	v_pk_mul_f32 v[90:91], v[94:95], v[98:99] op_sel_hi:[1,0]
	v_pk_mul_f32 v[92:93], v[96:97], v[98:99] op_sel_hi:[1,0]
	v_pk_mul_f32 v[94:95], v[104:105], v[98:99] op_sel_hi:[1,0]
	v_pk_fma_f32 v[92:93], v[148:149], v[92:93], v[152:153]
	v_pk_fma_f32 v[90:91], v[146:147], v[90:91], v[150:151]
	v_pk_mul_f32 v[96:97], v[102:103], v[98:99] op_sel_hi:[1,0]
	v_pk_fma_f32 v[94:95], v[154:155], v[94:95], v[158:159]
	v_pk_fma_f32 v[96:97], v[156:157], v[96:97], v[160:161]
	v_cvt_pk_bf16_f32 v90, v90, v91
	v_cvt_pk_bf16_f32 v91, v92, v93
	v_cvt_pk_bf16_f32 v92, v94, v95
	v_lshl_add_u64 v[94:95], v[100:101], 1, s[94:95]
	v_cvt_pk_bf16_f32 v93, v96, v97
	global_store_dwordx4 v[94:95], v[90:93], off
	s_nop 1
	v_pk_add_f32 v[90:91], v[84:85], v[162:163] op_sel_hi:[1,0]
	v_pk_add_f32 v[92:93], v[82:83], v[162:163] op_sel_hi:[1,0]
	v_cvt_pk_bf16_f32 v82, v86, v87
	v_cvt_pk_bf16_f32 v83, v88, v89
	s_nop 0
	v_cvt_pk_bf16_f32 v84, v92, v93
	v_cvt_pk_bf16_f32 v85, v90, v91
	global_store_dwordx4 v[106:107], v[82:85], off offset:256 sc1
	s_nop 1
	v_pk_mul_f32 v[82:83], v[86:87], v[98:99] op_sel_hi:[1,0]
	v_pk_mul_f32 v[84:85], v[88:89], v[98:99] op_sel_hi:[1,0]
	v_pk_fma_f32 v[82:83], v[130:131], v[82:83], v[134:135]
	v_pk_fma_f32 v[84:85], v[132:133], v[84:85], v[136:137]
	v_pk_mul_f32 v[86:87], v[92:93], v[98:99] op_sel_hi:[1,0]
	v_pk_mul_f32 v[88:89], v[90:91], v[98:99] op_sel_hi:[1,0]
	v_pk_fma_f32 v[86:87], v[138:139], v[86:87], v[142:143]
	v_pk_fma_f32 v[88:89], v[140:141], v[88:89], v[144:145]
	v_cvt_pk_bf16_f32 v82, v82, v83
	v_cvt_pk_bf16_f32 v83, v84, v85
	v_cvt_pk_bf16_f32 v84, v86, v87
	v_lshlrev_b64 v[90:91], 12, v[172:173]
	v_cvt_pk_bf16_f32 v85, v88, v89
	global_store_dwordx4 v[94:95], v[82:85], off offset:256
	ds_read_b32 v82, v188 offset:4288
	v_pk_add_f32 v[86:87], v[76:77], v[162:163] op_sel_hi:[1,0]
	v_pk_add_f32 v[88:89], v[74:75], v[162:163] op_sel_hi:[1,0]
	v_cvt_pk_bf16_f32 v74, v78, v79
	v_cvt_pk_bf16_f32 v75, v80, v81
	v_lshl_add_u64 v[90:91], v[178:179], 0, v[90:91]
	v_cvt_pk_bf16_f32 v76, v88, v89
	v_cvt_pk_bf16_f32 v77, v86, v87
	v_lshlrev_b64 v[84:85], 11, v[172:173]
	global_store_dwordx4 v[90:91], v[74:77], off sc1
	v_lshl_add_u64 v[84:85], v[84:85], 0, v[180:181]
	s_waitcnt lgkmcnt(0)
; __device__ __forceinline__ unsigned cvt_pk_bf16(float lo, float hi) { unsigned r; asm volatile("v_cvt_pk_bf16_f32 %0, %1, %2" : "=v"(r) : "v"(lo), "v"(hi)); return r; }
;     __device__ __forceinline__ void fused(f32x4 (&acc)[2][2][4][2], const Unit& u, int wr, int wc, int fr, int fq, PG8_LAS unsigned char* lds, int wid, int lane) const {
;     ...
; #pragma unroll
;         for (int ai = 0; ai < 2; ++ai)
; #pragma unroll
;             for (int m = 0; m < 4; ++m) { const int r = ai * HALF + wr * 64 + m * 16 + fr; const float rs = write_h ? S[r] : 0.0f; const size_t off = (size_t)(u.pm * BM + r) * 2048 + col0;
; #pragma unroll
;                 for (int bj = 0; bj < 2; ++bj) { const f32x4 x0 = acc[ai][bj][m][0] + poison, x1 = acc[ai][bj][m][1] + poison;
;                     if (out) { if (wofs == 0) { *(f32x4*)(out + off + bj * HALF) = x0; *(f32x4*)(out + off + bj * HALF + 4) = x1; } }
;                     else { u32x4 w; w.x = cvt_pk_bf16(x0[0], x0[1]); w.y = cvt_pk_bf16(x0[2], x0[3]); w.z = cvt_pk_bf16(x1[0], x1[1]); w.w = cvt_pk_bf16(x1[2], x1[3]); if (NT_FX) __builtin_nontemporal_store(w, (u32x4*)(X + wofs + off + bj * HALF)); else *(u32x4*)(X + wofs + off + bj * HALF) = w; }
;                     if (write_h) { const f32x4 h0 = x0 * rs * vs[bj][0] + vh[bj][0], h1 = x1 * rs * vs[bj][1] + vh[bj][1];
;                         u32x4 w; w.x = cvt_pk_bf16(h0[0], h0[1]); w.y = cvt_pk_bf16(h0[2], h0[3]); w.z = cvt_pk_bf16(h1[0], h1[1]); w.w = cvt_pk_bf16(h1[2], h1[3]); if (NT_FH) __builtin_nontemporal_store(w, (u32x4*)(H + wofs + off + bj * HALF)); else *(u32x4*)(H + wofs + off + bj * HALF) = w; } }
;                 asm volatile("" ::: "memory"); }
	v_pk_mul_f32 v[74:75], v[78:79], v[82:83] op_sel_hi:[1,0]
	v_pk_mul_f32 v[76:77], v[80:81], v[82:83] op_sel_hi:[1,0]
	v_pk_mul_f32 v[78:79], v[88:89], v[82:83] op_sel_hi:[1,0]
	v_pk_fma_f32 v[76:77], v[148:149], v[76:77], v[152:153]
	v_pk_fma_f32 v[74:75], v[146:147], v[74:75], v[150:151]
	v_pk_mul_f32 v[80:81], v[86:87], v[82:83] op_sel_hi:[1,0]
	v_pk_fma_f32 v[78:79], v[154:155], v[78:79], v[158:159]
	v_pk_fma_f32 v[80:81], v[156:157], v[80:81], v[160:161]
	v_cvt_pk_bf16_f32 v74, v74, v75
	v_cvt_pk_bf16_f32 v75, v76, v77
	v_cvt_pk_bf16_f32 v76, v78, v79
	v_lshl_add_u64 v[78:79], v[84:85], 1, s[94:95]
	v_cvt_pk_bf16_f32 v77, v80, v81
	global_store_dwordx4 v[78:79], v[74:77], off
	s_nop 1
	v_pk_add_f32 v[74:75], v[68:69], v[162:163] op_sel_hi:[1,0]
	v_pk_add_f32 v[76:77], v[66:67], v[162:163] op_sel_hi:[1,0]
	v_cvt_pk_bf16_f32 v66, v70, v71
	v_cvt_pk_bf16_f32 v67, v72, v73
	s_nop 0
	v_cvt_pk_bf16_f32 v68, v76, v77
	v_cvt_pk_bf16_f32 v69, v74, v75
	global_store_dwordx4 v[90:91], v[66:69], off offset:256 sc1
	s_nop 1
	v_pk_mul_f32 v[66:67], v[70:71], v[82:83] op_sel_hi:[1,0]
	v_pk_mul_f32 v[68:69], v[72:73], v[82:83] op_sel_hi:[1,0]
	v_pk_fma_f32 v[66:67], v[130:131], v[66:67], v[134:135]
	v_pk_fma_f32 v[68:69], v[132:133], v[68:69], v[136:137]
	v_pk_mul_f32 v[70:71], v[76:77], v[82:83] op_sel_hi:[1,0]
	v_pk_mul_f32 v[72:73], v[74:75], v[82:83] op_sel_hi:[1,0]
	v_pk_fma_f32 v[70:71], v[138:139], v[70:71], v[142:143]
	v_pk_fma_f32 v[72:73], v[140:141], v[72:73], v[144:145]
	v_cvt_pk_bf16_f32 v66, v66, v67
	v_cvt_pk_bf16_f32 v67, v68, v69
	v_cvt_pk_bf16_f32 v68, v70, v71
	v_lshlrev_b64 v[74:75], 12, v[170:171]
	v_cvt_pk_bf16_f32 v69, v72, v73
	global_store_dwordx4 v[78:79], v[66:69], off offset:256
	ds_read_b32 v66, v188 offset:4608
	v_pk_add_f32 v[70:71], v[60:61], v[162:163] op_sel_hi:[1,0]
	v_pk_add_f32 v[72:73], v[58:59], v[162:163] op_sel_hi:[1,0]
	v_cvt_pk_bf16_f32 v58, v62, v63
	v_cvt_pk_bf16_f32 v59, v64, v65
	v_lshl_add_u64 v[74:75], v[178:179], 0, v[74:75]
	v_cvt_pk_bf16_f32 v60, v72, v73
	v_cvt_pk_bf16_f32 v61, v70, v71
	v_lshlrev_b64 v[68:69], 11, v[170:171]
	global_store_dwordx4 v[74:75], v[58:61], off sc1
	v_lshl_add_u64 v[68:69], v[68:69], 0, v[180:181]
	s_waitcnt lgkmcnt(0)
	v_pk_mul_f32 v[58:59], v[62:63], v[66:67] op_sel_hi:[1,0]
	v_pk_mul_f32 v[60:61], v[64:65], v[66:67] op_sel_hi:[1,0]
	v_pk_mul_f32 v[62:63], v[72:73], v[66:67] op_sel_hi:[1,0]
	v_pk_fma_f32 v[60:61], v[148:149], v[60:61], v[152:153]
	v_pk_fma_f32 v[58:59], v[146:147], v[58:59], v[150:151]
	v_pk_mul_f32 v[64:65], v[70:71], v[66:67] op_sel_hi:[1,0]
	v_pk_fma_f32 v[62:63], v[154:155], v[62:63], v[158:159]
	v_pk_fma_f32 v[64:65], v[156:157], v[64:65], v[160:161]
	v_cvt_pk_bf16_f32 v58, v58, v59
	v_cvt_pk_bf16_f32 v59, v60, v61
	v_cvt_pk_bf16_f32 v60, v62, v63
	v_lshl_add_u64 v[62:63], v[68:69], 1, s[94:95]
	v_cvt_pk_bf16_f32 v61, v64, v65
	global_store_dwordx4 v[62:63], v[58:61], off
	s_nop 1
	v_pk_add_f32 v[58:59], v[52:53], v[162:163] op_sel_hi:[1,0]
	v_pk_add_f32 v[60:61], v[50:51], v[162:163] op_sel_hi:[1,0]
	v_cvt_pk_bf16_f32 v50, v54, v55
	v_cvt_pk_bf16_f32 v51, v56, v57
	s_nop 0
	v_cvt_pk_bf16_f32 v52, v60, v61
	v_cvt_pk_bf16_f32 v53, v58, v59
	global_store_dwordx4 v[74:75], v[50:53], off offset:256 sc1
	s_nop 1
	v_pk_mul_f32 v[50:51], v[54:55], v[66:67] op_sel_hi:[1,0]
	v_pk_mul_f32 v[52:53], v[56:57], v[66:67] op_sel_hi:[1,0]
	v_pk_fma_f32 v[50:51], v[130:131], v[50:51], v[134:135]
	v_pk_fma_f32 v[52:53], v[132:133], v[52:53], v[136:137]
	v_pk_mul_f32 v[54:55], v[60:61], v[66:67] op_sel_hi:[1,0]
	v_pk_mul_f32 v[56:57], v[58:59], v[66:67] op_sel_hi:[1,0]
	v_pk_fma_f32 v[54:55], v[138:139], v[54:55], v[142:143]
	v_pk_fma_f32 v[56:57], v[140:141], v[56:57], v[144:145]
	v_cvt_pk_bf16_f32 v50, v50, v51
	v_cvt_pk_bf16_f32 v51, v52, v53
	v_cvt_pk_bf16_f32 v52, v54, v55
	v_lshlrev_b64 v[58:59], 12, v[168:169]
	v_cvt_pk_bf16_f32 v53, v56, v57
	global_store_dwordx4 v[62:63], v[50:53], off offset:256
	ds_read_b32 v50, v188 offset:4672
	v_pk_add_f32 v[54:55], v[44:45], v[162:163] op_sel_hi:[1,0]
	v_pk_add_f32 v[56:57], v[42:43], v[162:163] op_sel_hi:[1,0]
	v_cvt_pk_bf16_f32 v42, v46, v47
	v_cvt_pk_bf16_f32 v43, v48, v49
	v_lshl_add_u64 v[58:59], v[178:179], 0, v[58:59]
	v_cvt_pk_bf16_f32 v44, v56, v57
	v_cvt_pk_bf16_f32 v45, v54, v55
	v_lshlrev_b64 v[52:53], 11, v[168:169]
	global_store_dwordx4 v[58:59], v[42:45], off sc1
	v_lshl_add_u64 v[52:53], v[52:53], 0, v[180:181]
	s_waitcnt lgkmcnt(0)
	v_pk_mul_f32 v[42:43], v[46:47], v[50:51] op_sel_hi:[1,0]
	v_pk_mul_f32 v[44:45], v[48:49], v[50:51] op_sel_hi:[1,0]
	v_pk_mul_f32 v[46:47], v[56:57], v[50:51] op_sel_hi:[1,0]
	v_pk_fma_f32 v[44:45], v[148:149], v[44:45], v[152:153]
	v_pk_fma_f32 v[42:43], v[146:147], v[42:43], v[150:151]
	v_pk_mul_f32 v[48:49], v[54:55], v[50:51] op_sel_hi:[1,0]
	v_pk_fma_f32 v[46:47], v[154:155], v[46:47], v[158:159]
	v_pk_fma_f32 v[48:49], v[156:157], v[48:49], v[160:161]
	v_cvt_pk_bf16_f32 v42, v42, v43
	v_cvt_pk_bf16_f32 v43, v44, v45
	v_cvt_pk_bf16_f32 v44, v46, v47
	v_lshl_add_u64 v[46:47], v[52:53], 1, s[94:95]
	v_cvt_pk_bf16_f32 v45, v48, v49
	global_store_dwordx4 v[46:47], v[42:45], off
	s_nop 1
	v_pk_add_f32 v[42:43], v[36:37], v[162:163] op_sel_hi:[1,0]
	v_pk_add_f32 v[44:45], v[34:35], v[162:163] op_sel_hi:[1,0]
	v_cvt_pk_bf16_f32 v34, v38, v39
	v_cvt_pk_bf16_f32 v35, v40, v41
	s_nop 0
	v_cvt_pk_bf16_f32 v36, v44, v45
	v_cvt_pk_bf16_f32 v37, v42, v43
	global_store_dwordx4 v[58:59], v[34:37], off offset:256 sc1
	s_nop 1
	v_pk_mul_f32 v[34:35], v[38:39], v[50:51] op_sel_hi:[1,0]
	v_pk_mul_f32 v[36:37], v[40:41], v[50:51] op_sel_hi:[1,0]
	v_pk_fma_f32 v[34:35], v[130:131], v[34:35], v[134:135]
	v_pk_fma_f32 v[36:37], v[132:133], v[36:37], v[136:137]
	v_pk_mul_f32 v[38:39], v[44:45], v[50:51] op_sel_hi:[1,0]
	v_pk_mul_f32 v[40:41], v[42:43], v[50:51] op_sel_hi:[1,0]
	v_pk_fma_f32 v[38:39], v[138:139], v[38:39], v[142:143]
	v_pk_fma_f32 v[40:41], v[140:141], v[40:41], v[144:145]
	v_cvt_pk_bf16_f32 v34, v34, v35
	v_cvt_pk_bf16_f32 v35, v36, v37
	v_cvt_pk_bf16_f32 v36, v38, v39
	v_lshlrev_b64 v[42:43], 12, v[166:167]
	v_cvt_pk_bf16_f32 v37, v40, v41
	global_store_dwordx4 v[46:47], v[34:37], off offset:256
	ds_read_b32 v34, v188 offset:4736
	v_pk_add_f32 v[38:39], v[28:29], v[162:163] op_sel_hi:[1,0]
	v_pk_add_f32 v[40:41], v[26:27], v[162:163] op_sel_hi:[1,0]
	v_cvt_pk_bf16_f32 v26, v30, v31
	v_cvt_pk_bf16_f32 v27, v32, v33
	v_lshl_add_u64 v[42:43], v[178:179], 0, v[42:43]
	v_cvt_pk_bf16_f32 v28, v40, v41
	v_cvt_pk_bf16_f32 v29, v38, v39
	v_lshlrev_b64 v[36:37], 11, v[166:167]
	global_store_dwordx4 v[42:43], v[26:29], off sc1
	v_lshl_add_u64 v[36:37], v[36:37], 0, v[180:181]
	s_waitcnt lgkmcnt(0)
; __device__ __forceinline__ unsigned cvt_pk_bf16(float lo, float hi) { unsigned r; asm volatile("v_cvt_pk_bf16_f32 %0, %1, %2" : "=v"(r) : "v"(lo), "v"(hi)); return r; }
;     __device__ __forceinline__ void fused(f32x4 (&acc)[2][2][4][2], const Unit& u, int wr, int wc, int fr, int fq, PG8_LAS unsigned char* lds, int wid, int lane) const {
;     ...
; #pragma unroll
;         for (int ai = 0; ai < 2; ++ai)
; #pragma unroll
;             for (int m = 0; m < 4; ++m) { const int r = ai * HALF + wr * 64 + m * 16 + fr; const float rs = write_h ? S[r] : 0.0f; const size_t off = (size_t)(u.pm * BM + r) * 2048 + col0;
; #pragma unroll
;                 for (int bj = 0; bj < 2; ++bj) { const f32x4 x0 = acc[ai][bj][m][0] + poison, x1 = acc[ai][bj][m][1] + poison;
;                     if (out) { if (wofs == 0) { *(f32x4*)(out + off + bj * HALF) = x0; *(f32x4*)(out + off + bj * HALF + 4) = x1; } }
;                     else { u32x4 w; w.x = cvt_pk_bf16(x0[0], x0[1]); w.y = cvt_pk_bf16(x0[2], x0[3]); w.z = cvt_pk_bf16(x1[0], x1[1]); w.w = cvt_pk_bf16(x1[2], x1[3]); if (NT_FX) __builtin_nontemporal_store(w, (u32x4*)(X + wofs + off + bj * HALF)); else *(u32x4*)(X + wofs + off + bj * HALF) = w; }
;                     if (write_h) { const f32x4 h0 = x0 * rs * vs[bj][0] + vh[bj][0], h1 = x1 * rs * vs[bj][1] + vh[bj][1];
;                         u32x4 w; w.x = cvt_pk_bf16(h0[0], h0[1]); w.y = cvt_pk_bf16(h0[2], h0[3]); w.z = cvt_pk_bf16(h1[0], h1[1]); w.w = cvt_pk_bf16(h1[2], h1[3]); if (NT_FH) __builtin_nontemporal_store(w, (u32x4*)(H + wofs + off + bj * HALF)); else *(u32x4*)(H + wofs + off + bj * HALF) = w; } }
;                 asm volatile("" ::: "memory"); }
; __device__ __forceinline__ void xcd_barrier(const XcdBarrier& b) {
;     asm volatile("s_waitcnt vmcnt(0)" ::: "memory");
;     __syncthreads();
;     if (threadIdx.x == 0) {
;         unsigned* bar = b.bar;
;         __builtin_amdgcn_s_waitcnt(0);
;         unsigned nloc = b.st[0], nx = b.st[1];
;         if (nloc == 0u) { xcd_barrier_complete(bar, b.x, nloc, nx); b.st[0] = nloc; b.st[1] = nx; }
	v_pk_mul_f32 v[26:27], v[30:31], v[34:35] op_sel_hi:[1,0]
	v_pk_mul_f32 v[28:29], v[32:33], v[34:35] op_sel_hi:[1,0]
	v_pk_mul_f32 v[30:31], v[40:41], v[34:35] op_sel_hi:[1,0]
	v_pk_fma_f32 v[28:29], v[148:149], v[28:29], v[152:153]
	v_pk_fma_f32 v[26:27], v[146:147], v[26:27], v[150:151]
	v_pk_mul_f32 v[32:33], v[38:39], v[34:35] op_sel_hi:[1,0]
	v_pk_fma_f32 v[30:31], v[154:155], v[30:31], v[158:159]
	v_pk_fma_f32 v[32:33], v[156:157], v[32:33], v[160:161]
	v_cvt_pk_bf16_f32 v26, v26, v27
	v_cvt_pk_bf16_f32 v27, v28, v29
	v_cvt_pk_bf16_f32 v28, v30, v31
	v_lshl_add_u64 v[30:31], v[36:37], 1, s[94:95]
	v_cvt_pk_bf16_f32 v29, v32, v33
	global_store_dwordx4 v[30:31], v[26:29], off
	s_nop 1
	v_pk_add_f32 v[26:27], v[20:21], v[162:163] op_sel_hi:[1,0]
	v_pk_add_f32 v[28:29], v[18:19], v[162:163] op_sel_hi:[1,0]
	v_cvt_pk_bf16_f32 v18, v22, v23
	v_cvt_pk_bf16_f32 v19, v24, v25
	s_nop 0
	v_cvt_pk_bf16_f32 v20, v28, v29
	v_cvt_pk_bf16_f32 v21, v26, v27
	global_store_dwordx4 v[42:43], v[18:21], off offset:256 sc1
	s_nop 1
	v_pk_mul_f32 v[18:19], v[22:23], v[34:35] op_sel_hi:[1,0]
	v_pk_mul_f32 v[20:21], v[24:25], v[34:35] op_sel_hi:[1,0]
	v_pk_fma_f32 v[18:19], v[130:131], v[18:19], v[134:135]
	v_pk_fma_f32 v[20:21], v[132:133], v[20:21], v[136:137]
	v_pk_mul_f32 v[22:23], v[28:29], v[34:35] op_sel_hi:[1,0]
	v_pk_mul_f32 v[24:25], v[26:27], v[34:35] op_sel_hi:[1,0]
	v_pk_fma_f32 v[22:23], v[138:139], v[22:23], v[142:143]
	v_pk_fma_f32 v[24:25], v[140:141], v[24:25], v[144:145]
	v_cvt_pk_bf16_f32 v18, v18, v19
	v_cvt_pk_bf16_f32 v19, v20, v21
	v_cvt_pk_bf16_f32 v20, v22, v23
	v_lshlrev_b64 v[26:27], 12, v[164:165]
	v_cvt_pk_bf16_f32 v21, v24, v25
	global_store_dwordx4 v[30:31], v[18:21], off offset:256
	ds_read_b32 v18, v188 offset:4800
	v_pk_add_f32 v[22:23], v[12:13], v[162:163] op_sel_hi:[1,0]
	v_pk_add_f32 v[24:25], v[10:11], v[162:163] op_sel_hi:[1,0]
	v_cvt_pk_bf16_f32 v10, v14, v15
	v_cvt_pk_bf16_f32 v11, v16, v17
	v_lshl_add_u64 v[26:27], v[178:179], 0, v[26:27]
	v_cvt_pk_bf16_f32 v12, v24, v25
	v_cvt_pk_bf16_f32 v13, v22, v23
	v_lshlrev_b64 v[20:21], 11, v[164:165]
	global_store_dwordx4 v[26:27], v[10:13], off sc1
	v_lshl_add_u64 v[20:21], v[20:21], 0, v[180:181]
	s_waitcnt lgkmcnt(0)
	v_pk_mul_f32 v[10:11], v[14:15], v[18:19] op_sel_hi:[1,0]
	v_pk_mul_f32 v[12:13], v[16:17], v[18:19] op_sel_hi:[1,0]
	v_pk_mul_f32 v[14:15], v[24:25], v[18:19] op_sel_hi:[1,0]
	v_pk_fma_f32 v[12:13], v[148:149], v[12:13], v[152:153]
	v_pk_fma_f32 v[10:11], v[146:147], v[10:11], v[150:151]
	v_pk_mul_f32 v[16:17], v[22:23], v[18:19] op_sel_hi:[1,0]
	v_pk_fma_f32 v[14:15], v[154:155], v[14:15], v[158:159]
	v_pk_fma_f32 v[16:17], v[156:157], v[16:17], v[160:161]
	v_cvt_pk_bf16_f32 v10, v10, v11
	v_cvt_pk_bf16_f32 v11, v12, v13
	v_cvt_pk_bf16_f32 v12, v14, v15
	v_lshl_add_u64 v[14:15], v[20:21], 1, s[94:95]
	v_cvt_pk_bf16_f32 v13, v16, v17
	global_store_dwordx4 v[14:15], v[10:13], off
	s_nop 1
	v_pk_add_f32 v[10:11], v[4:5], v[162:163] op_sel_hi:[1,0]
	v_pk_add_f32 v[12:13], v[2:3], v[162:163] op_sel_hi:[1,0]
	v_cvt_pk_bf16_f32 v2, v6, v7
	v_cvt_pk_bf16_f32 v3, v8, v9
	s_nop 0
	v_cvt_pk_bf16_f32 v4, v12, v13
	v_cvt_pk_bf16_f32 v5, v10, v11
	global_store_dwordx4 v[26:27], v[2:5], off offset:256 sc1
	s_nop 1
	v_pk_mul_f32 v[2:3], v[6:7], v[18:19] op_sel_hi:[1,0]
	v_pk_mul_f32 v[4:5], v[8:9], v[18:19] op_sel_hi:[1,0]
	v_pk_fma_f32 v[2:3], v[130:131], v[2:3], v[134:135]
	v_pk_fma_f32 v[4:5], v[132:133], v[4:5], v[136:137]
	v_pk_mul_f32 v[6:7], v[12:13], v[18:19] op_sel_hi:[1,0]
	v_pk_mul_f32 v[8:9], v[10:11], v[18:19] op_sel_hi:[1,0]
	v_pk_fma_f32 v[6:7], v[138:139], v[6:7], v[142:143]
	v_pk_fma_f32 v[8:9], v[140:141], v[8:9], v[144:145]
	v_cvt_pk_bf16_f32 v2, v2, v3
	v_cvt_pk_bf16_f32 v3, v4, v5
	v_cvt_pk_bf16_f32 v4, v6, v7
	s_nop 0
	v_cvt_pk_bf16_f32 v5, v8, v9
	global_store_dwordx4 v[14:15], v[2:5], off offset:256
	s_cbranch_scc1 .LBB0_1938
	s_waitcnt vmcnt(0)
	s_barrier
	s_and_saveexec_b64 s[0:1], s[92:93]
	s_cbranch_execz .LBB0_1937
	v_readlane_b32 s4, v254, 5
	s_waitcnt vmcnt(0) expcnt(0) lgkmcnt(0)
	s_nop 0
	v_mov_b32_e32 v2, s4
	ds_read_b32 v4, v2
	v_readlane_b32 s4, v254, 6
	s_waitcnt lgkmcnt(0)
	v_cmp_ne_u32_e32 vcc, 0, v4
	v_mov_b32_e32 v2, s4
	ds_read_b32 v2, v2
	s_cbranch_vccnz .LBB0_1901
	v_readlane_b32 s6, v250, 0
	v_readlane_b32 s7, v250, 1
	s_load_dwordx2 s[4:5], s[6:7], 0x4
	s_mov_b32 s11, 1
	s_waitcnt lgkmcnt(0)
	s_mul_i32 s10, s4, s33
	s_mul_i32 s10, s10, s5
	s_branch .LBB0_1889

; __device__ __forceinline__ unsigned cvt_pk_bf16(float lo, float hi) { unsigned r; asm volatile("v_cvt_pk_bf16_f32 %0, %1, %2" : "=v"(r) : "v"(lo), "v"(hi)); return r; }
;     __device__ __forceinline__ void fused(f32x4 (&acc)[2][2][4][2], const Unit& u, int wr, int wc, int fr, int fq, PG8_LAS unsigned char* lds, int wid, int lane) const {
;     ...
;                 for (int bj = 0; bj < 2; ++bj) { const f32x4 x0 = acc[ai][bj][m][0] + poison, x1 = acc[ai][bj][m][1] + poison;
;                     if (out) { if (wofs == 0) { *(f32x4*)(out + off + bj * HALF) = x0; *(f32x4*)(out + off + bj * HALF + 4) = x1; } }
;                     else { u32x4 w; w.x = cvt_pk_bf16(x0[0], x0[1]); w.y = cvt_pk_bf16(x0[2], x0[3]); w.z = cvt_pk_bf16(x1[0], x1[1]); w.w = cvt_pk_bf16(x1[2], x1[3]); if (NT_FX) __builtin_nontemporal_store(w, (u32x4*)(X + wofs + off + bj * HALF)); else *(u32x4*)(X + wofs + off + bj * HALF) = w; }
.LBB0_2429:
	v_cvt_pk_bf16_f32 v188, v126, v127
	v_cvt_pk_bf16_f32 v189, v128, v129
	v_cvt_pk_bf16_f32 v190, v122, v123
	v_cvt_pk_bf16_f32 v191, v124, v125
	global_store_dwordx4 v[172:173], v[188:191], off sc1

; __device__ __forceinline__ unsigned cvt_pk_bf16(float lo, float hi) { unsigned r; asm volatile("v_cvt_pk_bf16_f32 %0, %1, %2" : "=v"(r) : "v"(lo), "v"(hi)); return r; }
;     __device__ __forceinline__ void fused(f32x4 (&acc)[2][2][4][2], const Unit& u, int wr, int wc, int fr, int fq, PG8_LAS unsigned char* lds, int wid, int lane) const {
;     ...
;                 for (int bj = 0; bj < 2; ++bj) { const f32x4 x0 = acc[ai][bj][m][0] + poison, x1 = acc[ai][bj][m][1] + poison;
;                     if (out) { if (wofs == 0) { *(f32x4*)(out + off + bj * HALF) = x0; *(f32x4*)(out + off + bj * HALF + 4) = x1; } }
;                     else { u32x4 w; w.x = cvt_pk_bf16(x0[0], x0[1]); w.y = cvt_pk_bf16(x0[2], x0[3]); w.z = cvt_pk_bf16(x1[0], x1[1]); w.w = cvt_pk_bf16(x1[2], x1[3]); if (NT_FX) __builtin_nontemporal_store(w, (u32x4*)(X + wofs + off + bj * HALF)); else *(u32x4*)(X + wofs + off + bj * HALF) = w; }
.LBB0_2434:
	v_cvt_pk_bf16_f32 v122, v118, v119
	v_cvt_pk_bf16_f32 v123, v120, v121
	v_cvt_pk_bf16_f32 v124, v114, v115
	v_cvt_pk_bf16_f32 v125, v116, v117
	global_store_dwordx4 v[172:173], v[122:125], off offset:256 sc1

; __device__ __forceinline__ unsigned cvt_pk_bf16(float lo, float hi) { unsigned r; asm volatile("v_cvt_pk_bf16_f32 %0, %1, %2" : "=v"(r) : "v"(lo), "v"(hi)); return r; }
;     __device__ __forceinline__ void fused(f32x4 (&acc)[2][2][4][2], const Unit& u, int wr, int wc, int fr, int fq, PG8_LAS unsigned char* lds, int wid, int lane) const {
;     ...
;                 for (int bj = 0; bj < 2; ++bj) { const f32x4 x0 = acc[ai][bj][m][0] + poison, x1 = acc[ai][bj][m][1] + poison;
;                     if (out) { if (wofs == 0) { *(f32x4*)(out + off + bj * HALF) = x0; *(f32x4*)(out + off + bj * HALF + 4) = x1; } }
;                     else { u32x4 w; w.x = cvt_pk_bf16(x0[0], x0[1]); w.y = cvt_pk_bf16(x0[2], x0[3]); w.z = cvt_pk_bf16(x1[0], x1[1]); w.w = cvt_pk_bf16(x1[2], x1[3]); if (NT_FX) __builtin_nontemporal_store(w, (u32x4*)(X + wofs + off + bj * HALF)); else *(u32x4*)(X + wofs + off + bj * HALF) = w; }
.LBB0_2441:
	v_cvt_pk_bf16_f32 v122, v110, v111
	v_cvt_pk_bf16_f32 v123, v112, v113
	v_cvt_pk_bf16_f32 v124, v106, v107
	v_cvt_pk_bf16_f32 v125, v108, v109
	global_store_dwordx4 v[118:119], v[122:125], off sc1

; __device__ __forceinline__ unsigned cvt_pk_bf16(float lo, float hi) { unsigned r; asm volatile("v_cvt_pk_bf16_f32 %0, %1, %2" : "=v"(r) : "v"(lo), "v"(hi)); return r; }
;     __device__ __forceinline__ void fused(f32x4 (&acc)[2][2][4][2], const Unit& u, int wr, int wc, int fr, int fq, PG8_LAS unsigned char* lds, int wid, int lane) const {
;     ...
;                 for (int bj = 0; bj < 2; ++bj) { const f32x4 x0 = acc[ai][bj][m][0] + poison, x1 = acc[ai][bj][m][1] + poison;
;                     if (out) { if (wofs == 0) { *(f32x4*)(out + off + bj * HALF) = x0; *(f32x4*)(out + off + bj * HALF + 4) = x1; } }
;                     else { u32x4 w; w.x = cvt_pk_bf16(x0[0], x0[1]); w.y = cvt_pk_bf16(x0[2], x0[3]); w.z = cvt_pk_bf16(x1[0], x1[1]); w.w = cvt_pk_bf16(x1[2], x1[3]); if (NT_FX) __builtin_nontemporal_store(w, (u32x4*)(X + wofs + off + bj * HALF)); else *(u32x4*)(X + wofs + off + bj * HALF) = w; }
.LBB0_2446:
	v_cvt_pk_bf16_f32 v106, v102, v103
	v_cvt_pk_bf16_f32 v107, v104, v105
	v_cvt_pk_bf16_f32 v108, v98, v99
	v_cvt_pk_bf16_f32 v109, v100, v101
	global_store_dwordx4 v[118:119], v[106:109], off offset:256 sc1

; __device__ __forceinline__ unsigned cvt_pk_bf16(float lo, float hi) { unsigned r; asm volatile("v_cvt_pk_bf16_f32 %0, %1, %2" : "=v"(r) : "v"(lo), "v"(hi)); return r; }
;     __device__ __forceinline__ void fused(f32x4 (&acc)[2][2][4][2], const Unit& u, int wr, int wc, int fr, int fq, PG8_LAS unsigned char* lds, int wid, int lane) const {
;     ...
;                 for (int bj = 0; bj < 2; ++bj) { const f32x4 x0 = acc[ai][bj][m][0] + poison, x1 = acc[ai][bj][m][1] + poison;
;                     if (out) { if (wofs == 0) { *(f32x4*)(out + off + bj * HALF) = x0; *(f32x4*)(out + off + bj * HALF + 4) = x1; } }
;                     else { u32x4 w; w.x = cvt_pk_bf16(x0[0], x0[1]); w.y = cvt_pk_bf16(x0[2], x0[3]); w.z = cvt_pk_bf16(x1[0], x1[1]); w.w = cvt_pk_bf16(x1[2], x1[3]); if (NT_FX) __builtin_nontemporal_store(w, (u32x4*)(X + wofs + off + bj * HALF)); else *(u32x4*)(X + wofs + off + bj * HALF) = w; }
.LBB0_2453:
	v_cvt_pk_bf16_f32 v106, v94, v95
	v_cvt_pk_bf16_f32 v107, v96, v97
	v_cvt_pk_bf16_f32 v108, v90, v91
	v_cvt_pk_bf16_f32 v109, v92, v93
	global_store_dwordx4 v[102:103], v[106:109], off sc1

; __device__ __forceinline__ unsigned cvt_pk_bf16(float lo, float hi) { unsigned r; asm volatile("v_cvt_pk_bf16_f32 %0, %1, %2" : "=v"(r) : "v"(lo), "v"(hi)); return r; }
;     __device__ __forceinline__ void fused(f32x4 (&acc)[2][2][4][2], const Unit& u, int wr, int wc, int fr, int fq, PG8_LAS unsigned char* lds, int wid, int lane) const {
;     ...
;                 for (int bj = 0; bj < 2; ++bj) { const f32x4 x0 = acc[ai][bj][m][0] + poison, x1 = acc[ai][bj][m][1] + poison;
;                     if (out) { if (wofs == 0) { *(f32x4*)(out + off + bj * HALF) = x0; *(f32x4*)(out + off + bj * HALF + 4) = x1; } }
;                     else { u32x4 w; w.x = cvt_pk_bf16(x0[0], x0[1]); w.y = cvt_pk_bf16(x0[2], x0[3]); w.z = cvt_pk_bf16(x1[0], x1[1]); w.w = cvt_pk_bf16(x1[2], x1[3]); if (NT_FX) __builtin_nontemporal_store(w, (u32x4*)(X + wofs + off + bj * HALF)); else *(u32x4*)(X + wofs + off + bj * HALF) = w; }
.LBB0_2458:
	v_cvt_pk_bf16_f32 v90, v86, v87
	v_cvt_pk_bf16_f32 v91, v88, v89
	v_cvt_pk_bf16_f32 v92, v82, v83
	v_cvt_pk_bf16_f32 v93, v84, v85
	global_store_dwordx4 v[102:103], v[90:93], off offset:256 sc1

; __device__ __forceinline__ unsigned cvt_pk_bf16(float lo, float hi) { unsigned r; asm volatile("v_cvt_pk_bf16_f32 %0, %1, %2" : "=v"(r) : "v"(lo), "v"(hi)); return r; }
;     __device__ __forceinline__ void fused(f32x4 (&acc)[2][2][4][2], const Unit& u, int wr, int wc, int fr, int fq, PG8_LAS unsigned char* lds, int wid, int lane) const {
;     ...
;                 for (int bj = 0; bj < 2; ++bj) { const f32x4 x0 = acc[ai][bj][m][0] + poison, x1 = acc[ai][bj][m][1] + poison;
;                     if (out) { if (wofs == 0) { *(f32x4*)(out + off + bj * HALF) = x0; *(f32x4*)(out + off + bj * HALF + 4) = x1; } }
;                     else { u32x4 w; w.x = cvt_pk_bf16(x0[0], x0[1]); w.y = cvt_pk_bf16(x0[2], x0[3]); w.z = cvt_pk_bf16(x1[0], x1[1]); w.w = cvt_pk_bf16(x1[2], x1[3]); if (NT_FX) __builtin_nontemporal_store(w, (u32x4*)(X + wofs + off + bj * HALF)); else *(u32x4*)(X + wofs + off + bj * HALF) = w; }
.LBB0_2465:
	v_cvt_pk_bf16_f32 v90, v78, v79
	v_cvt_pk_bf16_f32 v91, v80, v81
	v_cvt_pk_bf16_f32 v92, v74, v75
	v_cvt_pk_bf16_f32 v93, v76, v77
	global_store_dwordx4 v[86:87], v[90:93], off sc1

; __device__ __forceinline__ unsigned cvt_pk_bf16(float lo, float hi) { unsigned r; asm volatile("v_cvt_pk_bf16_f32 %0, %1, %2" : "=v"(r) : "v"(lo), "v"(hi)); return r; }
;     __device__ __forceinline__ void fused(f32x4 (&acc)[2][2][4][2], const Unit& u, int wr, int wc, int fr, int fq, PG8_LAS unsigned char* lds, int wid, int lane) const {
;     ...
;                 for (int bj = 0; bj < 2; ++bj) { const f32x4 x0 = acc[ai][bj][m][0] + poison, x1 = acc[ai][bj][m][1] + poison;
;                     if (out) { if (wofs == 0) { *(f32x4*)(out + off + bj * HALF) = x0; *(f32x4*)(out + off + bj * HALF + 4) = x1; } }
;                     else { u32x4 w; w.x = cvt_pk_bf16(x0[0], x0[1]); w.y = cvt_pk_bf16(x0[2], x0[3]); w.z = cvt_pk_bf16(x1[0], x1[1]); w.w = cvt_pk_bf16(x1[2], x1[3]); if (NT_FX) __builtin_nontemporal_store(w, (u32x4*)(X + wofs + off + bj * HALF)); else *(u32x4*)(X + wofs + off + bj * HALF) = w; }
.LBB0_2470:
	v_cvt_pk_bf16_f32 v74, v70, v71
	v_cvt_pk_bf16_f32 v75, v72, v73
	v_cvt_pk_bf16_f32 v76, v66, v67
	v_cvt_pk_bf16_f32 v77, v68, v69
	global_store_dwordx4 v[86:87], v[74:77], off offset:256 sc1

; __device__ __forceinline__ unsigned cvt_pk_bf16(float lo, float hi) { unsigned r; asm volatile("v_cvt_pk_bf16_f32 %0, %1, %2" : "=v"(r) : "v"(lo), "v"(hi)); return r; }
;     __device__ __forceinline__ void fused(f32x4 (&acc)[2][2][4][2], const Unit& u, int wr, int wc, int fr, int fq, PG8_LAS unsigned char* lds, int wid, int lane) const {
;     ...
;                 for (int bj = 0; bj < 2; ++bj) { const f32x4 x0 = acc[ai][bj][m][0] + poison, x1 = acc[ai][bj][m][1] + poison;
;                     if (out) { if (wofs == 0) { *(f32x4*)(out + off + bj * HALF) = x0; *(f32x4*)(out + off + bj * HALF + 4) = x1; } }
;                     else { u32x4 w; w.x = cvt_pk_bf16(x0[0], x0[1]); w.y = cvt_pk_bf16(x0[2], x0[3]); w.z = cvt_pk_bf16(x1[0], x1[1]); w.w = cvt_pk_bf16(x1[2], x1[3]); if (NT_FX) __builtin_nontemporal_store(w, (u32x4*)(X + wofs + off + bj * HALF)); else *(u32x4*)(X + wofs + off + bj * HALF) = w; }
.LBB0_2477:
	v_cvt_pk_bf16_f32 v74, v62, v63
	v_cvt_pk_bf16_f32 v75, v64, v65
	v_cvt_pk_bf16_f32 v76, v58, v59
	v_cvt_pk_bf16_f32 v77, v60, v61
	global_store_dwordx4 v[70:71], v[74:77], off sc1

; __device__ __forceinline__ unsigned cvt_pk_bf16(float lo, float hi) { unsigned r; asm volatile("v_cvt_pk_bf16_f32 %0, %1, %2" : "=v"(r) : "v"(lo), "v"(hi)); return r; }
;     __device__ __forceinline__ void fused(f32x4 (&acc)[2][2][4][2], const Unit& u, int wr, int wc, int fr, int fq, PG8_LAS unsigned char* lds, int wid, int lane) const {
;     ...
;                 for (int bj = 0; bj < 2; ++bj) { const f32x4 x0 = acc[ai][bj][m][0] + poison, x1 = acc[ai][bj][m][1] + poison;
;                     if (out) { if (wofs == 0) { *(f32x4*)(out + off + bj * HALF) = x0; *(f32x4*)(out + off + bj * HALF + 4) = x1; } }
;                     else { u32x4 w; w.x = cvt_pk_bf16(x0[0], x0[1]); w.y = cvt_pk_bf16(x0[2], x0[3]); w.z = cvt_pk_bf16(x1[0], x1[1]); w.w = cvt_pk_bf16(x1[2], x1[3]); if (NT_FX) __builtin_nontemporal_store(w, (u32x4*)(X + wofs + off + bj * HALF)); else *(u32x4*)(X + wofs + off + bj * HALF) = w; }
.LBB0_2482:
	v_cvt_pk_bf16_f32 v58, v54, v55
	v_cvt_pk_bf16_f32 v59, v56, v57
	v_cvt_pk_bf16_f32 v60, v50, v51
	v_cvt_pk_bf16_f32 v61, v52, v53
	global_store_dwordx4 v[70:71], v[58:61], off offset:256 sc1

; __device__ __forceinline__ unsigned cvt_pk_bf16(float lo, float hi) { unsigned r; asm volatile("v_cvt_pk_bf16_f32 %0, %1, %2" : "=v"(r) : "v"(lo), "v"(hi)); return r; }
;     __device__ __forceinline__ void fused(f32x4 (&acc)[2][2][4][2], const Unit& u, int wr, int wc, int fr, int fq, PG8_LAS unsigned char* lds, int wid, int lane) const {
;     ...
;                 for (int bj = 0; bj < 2; ++bj) { const f32x4 x0 = acc[ai][bj][m][0] + poison, x1 = acc[ai][bj][m][1] + poison;
;                     if (out) { if (wofs == 0) { *(f32x4*)(out + off + bj * HALF) = x0; *(f32x4*)(out + off + bj * HALF + 4) = x1; } }
;                     else { u32x4 w; w.x = cvt_pk_bf16(x0[0], x0[1]); w.y = cvt_pk_bf16(x0[2], x0[3]); w.z = cvt_pk_bf16(x1[0], x1[1]); w.w = cvt_pk_bf16(x1[2], x1[3]); if (NT_FX) __builtin_nontemporal_store(w, (u32x4*)(X + wofs + off + bj * HALF)); else *(u32x4*)(X + wofs + off + bj * HALF) = w; }
.LBB0_2489:
	v_cvt_pk_bf16_f32 v58, v46, v47
	v_cvt_pk_bf16_f32 v59, v48, v49
	v_cvt_pk_bf16_f32 v60, v42, v43
	v_cvt_pk_bf16_f32 v61, v44, v45
	global_store_dwordx4 v[54:55], v[58:61], off sc1

; __device__ __forceinline__ unsigned cvt_pk_bf16(float lo, float hi) { unsigned r; asm volatile("v_cvt_pk_bf16_f32 %0, %1, %2" : "=v"(r) : "v"(lo), "v"(hi)); return r; }
;     __device__ __forceinline__ void fused(f32x4 (&acc)[2][2][4][2], const Unit& u, int wr, int wc, int fr, int fq, PG8_LAS unsigned char* lds, int wid, int lane) const {
;     ...
;                 for (int bj = 0; bj < 2; ++bj) { const f32x4 x0 = acc[ai][bj][m][0] + poison, x1 = acc[ai][bj][m][1] + poison;
;                     if (out) { if (wofs == 0) { *(f32x4*)(out + off + bj * HALF) = x0; *(f32x4*)(out + off + bj * HALF + 4) = x1; } }
;                     else { u32x4 w; w.x = cvt_pk_bf16(x0[0], x0[1]); w.y = cvt_pk_bf16(x0[2], x0[3]); w.z = cvt_pk_bf16(x1[0], x1[1]); w.w = cvt_pk_bf16(x1[2], x1[3]); if (NT_FX) __builtin_nontemporal_store(w, (u32x4*)(X + wofs + off + bj * HALF)); else *(u32x4*)(X + wofs + off + bj * HALF) = w; }
.LBB0_2494:
	v_cvt_pk_bf16_f32 v42, v38, v39
	v_cvt_pk_bf16_f32 v43, v40, v41
	v_cvt_pk_bf16_f32 v44, v34, v35
	v_cvt_pk_bf16_f32 v45, v36, v37
	global_store_dwordx4 v[54:55], v[42:45], off offset:256 sc1

; __device__ __forceinline__ unsigned cvt_pk_bf16(float lo, float hi) { unsigned r; asm volatile("v_cvt_pk_bf16_f32 %0, %1, %2" : "=v"(r) : "v"(lo), "v"(hi)); return r; }
;     __device__ __forceinline__ void fused(f32x4 (&acc)[2][2][4][2], const Unit& u, int wr, int wc, int fr, int fq, PG8_LAS unsigned char* lds, int wid, int lane) const {
;     ...
;                 for (int bj = 0; bj < 2; ++bj) { const f32x4 x0 = acc[ai][bj][m][0] + poison, x1 = acc[ai][bj][m][1] + poison;
;                     if (out) { if (wofs == 0) { *(f32x4*)(out + off + bj * HALF) = x0; *(f32x4*)(out + off + bj * HALF + 4) = x1; } }
;                     else { u32x4 w; w.x = cvt_pk_bf16(x0[0], x0[1]); w.y = cvt_pk_bf16(x0[2], x0[3]); w.z = cvt_pk_bf16(x1[0], x1[1]); w.w = cvt_pk_bf16(x1[2], x1[3]); if (NT_FX) __builtin_nontemporal_store(w, (u32x4*)(X + wofs + off + bj * HALF)); else *(u32x4*)(X + wofs + off + bj * HALF) = w; }
.LBB0_2501:
	v_cvt_pk_bf16_f32 v42, v30, v31
	v_cvt_pk_bf16_f32 v43, v32, v33
	v_cvt_pk_bf16_f32 v44, v26, v27
	v_cvt_pk_bf16_f32 v45, v28, v29
	global_store_dwordx4 v[38:39], v[42:45], off sc1

; __device__ __forceinline__ unsigned cvt_pk_bf16(float lo, float hi) { unsigned r; asm volatile("v_cvt_pk_bf16_f32 %0, %1, %2" : "=v"(r) : "v"(lo), "v"(hi)); return r; }
;     __device__ __forceinline__ void fused(f32x4 (&acc)[2][2][4][2], const Unit& u, int wr, int wc, int fr, int fq, PG8_LAS unsigned char* lds, int wid, int lane) const {
;     ...
;                 for (int bj = 0; bj < 2; ++bj) { const f32x4 x0 = acc[ai][bj][m][0] + poison, x1 = acc[ai][bj][m][1] + poison;
;                     if (out) { if (wofs == 0) { *(f32x4*)(out + off + bj * HALF) = x0; *(f32x4*)(out + off + bj * HALF + 4) = x1; } }
;                     else { u32x4 w; w.x = cvt_pk_bf16(x0[0], x0[1]); w.y = cvt_pk_bf16(x0[2], x0[3]); w.z = cvt_pk_bf16(x1[0], x1[1]); w.w = cvt_pk_bf16(x1[2], x1[3]); if (NT_FX) __builtin_nontemporal_store(w, (u32x4*)(X + wofs + off + bj * HALF)); else *(u32x4*)(X + wofs + off + bj * HALF) = w; }
.LBB0_2506:
	v_cvt_pk_bf16_f32 v26, v22, v23
	v_cvt_pk_bf16_f32 v27, v24, v25
	v_cvt_pk_bf16_f32 v28, v18, v19
	v_cvt_pk_bf16_f32 v29, v20, v21
	global_store_dwordx4 v[38:39], v[26:29], off offset:256 sc1

; __device__ __forceinline__ unsigned cvt_pk_bf16(float lo, float hi) { unsigned r; asm volatile("v_cvt_pk_bf16_f32 %0, %1, %2" : "=v"(r) : "v"(lo), "v"(hi)); return r; }
;     __device__ __forceinline__ void fused(f32x4 (&acc)[2][2][4][2], const Unit& u, int wr, int wc, int fr, int fq, PG8_LAS unsigned char* lds, int wid, int lane) const {
;     ...
;                 for (int bj = 0; bj < 2; ++bj) { const f32x4 x0 = acc[ai][bj][m][0] + poison, x1 = acc[ai][bj][m][1] + poison;
;                     if (out) { if (wofs == 0) { *(f32x4*)(out + off + bj * HALF) = x0; *(f32x4*)(out + off + bj * HALF + 4) = x1; } }
;                     else { u32x4 w; w.x = cvt_pk_bf16(x0[0], x0[1]); w.y = cvt_pk_bf16(x0[2], x0[3]); w.z = cvt_pk_bf16(x1[0], x1[1]); w.w = cvt_pk_bf16(x1[2], x1[3]); if (NT_FX) __builtin_nontemporal_store(w, (u32x4*)(X + wofs + off + bj * HALF)); else *(u32x4*)(X + wofs + off + bj * HALF) = w; }
.LBB0_2513:
	v_cvt_pk_bf16_f32 v26, v14, v15
	v_cvt_pk_bf16_f32 v27, v16, v17
	v_cvt_pk_bf16_f32 v28, v10, v11
	v_cvt_pk_bf16_f32 v29, v12, v13
	global_store_dwordx4 v[22:23], v[26:29], off sc1

; __device__ __forceinline__ unsigned cvt_pk_bf16(float lo, float hi) { unsigned r; asm volatile("v_cvt_pk_bf16_f32 %0, %1, %2" : "=v"(r) : "v"(lo), "v"(hi)); return r; }
;     __device__ __forceinline__ void fused(f32x4 (&acc)[2][2][4][2], const Unit& u, int wr, int wc, int fr, int fq, PG8_LAS unsigned char* lds, int wid, int lane) const {
;     ...
;                 for (int bj = 0; bj < 2; ++bj) { const f32x4 x0 = acc[ai][bj][m][0] + poison, x1 = acc[ai][bj][m][1] + poison;
;                     if (out) { if (wofs == 0) { *(f32x4*)(out + off + bj * HALF) = x0; *(f32x4*)(out + off + bj * HALF + 4) = x1; } }
;                     else { u32x4 w; w.x = cvt_pk_bf16(x0[0], x0[1]); w.y = cvt_pk_bf16(x0[2], x0[3]); w.z = cvt_pk_bf16(x1[0], x1[1]); w.w = cvt_pk_bf16(x1[2], x1[3]); if (NT_FX) __builtin_nontemporal_store(w, (u32x4*)(X + wofs + off + bj * HALF)); else *(u32x4*)(X + wofs + off + bj * HALF) = w; }
.LBB0_2518:
	v_cvt_pk_bf16_f32 v10, v6, v7
	v_cvt_pk_bf16_f32 v11, v8, v9
	v_cvt_pk_bf16_f32 v12, v2, v3
	v_cvt_pk_bf16_f32 v13, v4, v5
	global_store_dwordx4 v[22:23], v[10:13], off offset:256 sc1
